# GEMM K-loops: post-MFMA m0/address bookkeeping hoisted into the same phase's load segment (before the barrier that opens the MFMA burst), MFMA tail is now burst then barrier
# speedup vs baseline: 1.0202x; 1.0062x over previous
; #define PG8_STAGE(bufoff, gbase, v0, v1) do { \
;         __builtin_amdgcn_global_load_lds((const unsigned*)((const char*)(gbase) + (v0)), (LAS unsigned*)(lds + (bufoff) + ldsw), 16, 0, 0); \
;         __builtin_amdgcn_global_load_lds((const unsigned*)((const char*)(gbase) + (v1)), (LAS unsigned*)(lds + (bufoff) + ldsw + 8192), 16, 0, 0); } while (0)
; #define PG8_LDA(dst, b, h) do { _Pragma("unroll") for (int m = 0; m < 4; ++m) _Pragma("unroll") for (int k = 0; k < 2; ++k) dst[m][k] = *(const LAS bf16x8*)(lds + PG8_SA(b, h) + aoff + m * 2048 + k * 1024); } while (0)
; #define PG8_LDB(dst, b, h) do { _Pragma("unroll") for (int n = 0; n < 2; ++n) _Pragma("unroll") for (int k = 0; k < 2; ++k) dst[n][k] = *(const LAS bf16x8*)(lds + PG8_SB(b, h) + boff + n * 2048 + k * 1024); } while (0)
; #define PG8_MMA(ai, bj, At, Bt) do { __builtin_amdgcn_s_setprio(1); _Pragma("unroll") for (int m = 0; m < 4; ++m) _Pragma("unroll") for (int n = 0; n < 2; ++n) _Pragma("unroll") for (int k = 0; k < 2; ++k) \
;         acc[ai][bj][m][n] = __builtin_amdgcn_mfma_f32_16x16x32_bf16(Bt[n][k], At[m][k], acc[ai][bj][m][n], 0, 0, 0); __builtin_amdgcn_s_setprio(0); } while (0)
; #define PG8_WAIT_V(n) asm volatile("s_waitcnt vmcnt(" #n ")" ::: "memory")
; #define PG8_WAIT_L(n) asm volatile("s_waitcnt lgkmcnt(" #n ")" ::: "memory")
; #define PG8_BAR __builtin_amdgcn_s_barrier()
; #define PG8_SCHED __builtin_amdgcn_sched_barrier(0)
; template <class Epi, class Sched>
; __device__ __forceinline__ void gemm_phase(LAS unsigned char* lds, const Sched& S, const Epi& E) {
;     ...
;             PG8_LDB(B0, 0, 0); PG8_SCHED; PG8_LDA(At, 0, 0); PG8_STAGE(PG8_SA(1, 1), a1 + hA, vA0, vA1);
;             PG8_WAIT_L(8); PG8_BAR; PG8_WAIT_L(0); PG8_MMA(0, 0, At, B0); PG8_BAR; PG8_SCHED;
;             PG8_LDB(B1, 0, 1); PG8_STAGE(PG8_SB(0, 0), b2, xB0, xB1);
;             PG8_BAR; PG8_WAIT_L(0); PG8_MMA(0, 1, At, B1); PG8_BAR;
;             PG8_LDA(At, 0, 1); PG8_STAGE(PG8_SA(0, 0), a2, xA0, xA1);
;             PG8_BAR; PG8_WAIT_L(0); PG8_MMA(1, 0, At, B0); PG8_BAR; PG8_SCHED;
;             PG8_STAGE(PG8_SB(0, 1), b2 + xhB, xB0, xB1);
;             PG8_WAIT_V(6); PG8_BAR; PG8_MMA(1, 1, At, B1); PG8_BAR;
.Lrot_body_0:
	ds_read_b128 v[158:161], v138
	ds_read_b128 v[182:185], v138 offset:1024
	ds_read_b128 v[186:189], v138 offset:2048
	ds_read_b128 v[190:193], v138 offset:3072
	v_lshl_add_u64 v[226:227], s[26:27], 0, v[132:133]
	s_add_i32 m0, s48, 0xc000
	ds_read_b128 v[194:197], v154
	ds_read_b128 v[198:201], v154 offset:1024
	ds_read_b128 v[202:205], v154 offset:2048
	ds_read_b128 v[206:209], v154 offset:3072
	ds_read_b128 v[210:213], v154 offset:4096
	ds_read_b128 v[214:217], v154 offset:5120
	ds_read_b128 v[218:221], v154 offset:6144
	ds_read_b128 v[222:225], v154 offset:7168
	global_load_lds_dwordx4 v[226:227], off
	v_lshl_add_u64 v[226:227], s[26:27], 0, v[134:135]
	s_add_i32 m0, s48, 0xe000
	s_nop 0
	global_load_lds_dwordx4 v[226:227], off
	s_waitcnt lgkmcnt(8)
	s_barrier
	s_waitcnt lgkmcnt(0)
	v_mfma_f32_16x16x32_bf16 v[124:127], v[158:161], v[194:197], v[124:127]
	v_mfma_f32_16x16x32_bf16 v[120:123], v[186:189], v[194:197], v[120:123]
	v_mfma_f32_16x16x32_bf16 v[116:119], v[158:161], v[202:205], v[116:119]
	v_mfma_f32_16x16x32_bf16 v[112:115], v[186:189], v[202:205], v[112:115]
	v_mfma_f32_16x16x32_bf16 v[100:103], v[158:161], v[210:213], v[100:103]
	v_mfma_f32_16x16x32_bf16 v[96:99], v[186:189], v[210:213], v[96:99]
	v_mfma_f32_16x16x32_bf16 v[84:87], v[158:161], v[218:221], v[84:87]
	v_mfma_f32_16x16x32_bf16 v[80:83], v[186:189], v[218:221], v[80:83]
	v_mfma_f32_16x16x32_bf16 v[124:127], v[182:185], v[198:201], v[124:127]
	v_mfma_f32_16x16x32_bf16 v[120:123], v[190:193], v[198:201], v[120:123]
	v_mfma_f32_16x16x32_bf16 v[116:119], v[182:185], v[206:209], v[116:119]
	v_mfma_f32_16x16x32_bf16 v[112:115], v[190:193], v[206:209], v[112:115]
	v_mfma_f32_16x16x32_bf16 v[100:103], v[182:185], v[214:217], v[100:103]
	v_mfma_f32_16x16x32_bf16 v[96:99], v[190:193], v[214:217], v[96:99]
	v_mfma_f32_16x16x32_bf16 v[84:87], v[182:185], v[222:225], v[84:87]
	v_mfma_f32_16x16x32_bf16 v[80:83], v[190:193], v[222:225], v[80:83]
	s_barrier
	s_add_i32 s69, 0, 0x14000
	s_add_i32 s21, s21, s43
	v_add_u32_e32 v138, s69, v153
	s_mov_b32 m0, s21
	ds_read_b128 v[226:229], v138
	ds_read_b128 v[230:233], v138 offset:1024
	ds_read_b128 v[234:237], v138 offset:2048
	ds_read_b128 v[238:241], v138 offset:3072
	global_load_lds_dwordx4 v136, s[38:39]
	s_add_i32 m0, s21, 0x2000
	v_mov_b32_e32 v147, v137
	global_load_lds_dwordx4 v146, s[38:39]
	v_lshl_add_u64 v[242:243], s[38:39], 0, v[136:137]
	v_lshl_add_u64 v[244:245], s[38:39], 0, v[146:147]
	s_mov_b32 m0, s48
	v_lshl_add_u64 v[246:247], s[40:41], 0, v[150:151]
	s_barrier
	s_waitcnt lgkmcnt(0)
	v_mfma_f32_16x16x32_bf16 v[108:111], v[226:229], v[194:197], v[108:111]
	v_mfma_f32_16x16x32_bf16 v[104:107], v[234:237], v[194:197], v[104:107]
	v_mfma_f32_16x16x32_bf16 v[92:95], v[226:229], v[202:205], v[92:95]
	v_mfma_f32_16x16x32_bf16 v[88:91], v[234:237], v[202:205], v[88:91]
	v_mfma_f32_16x16x32_bf16 v[76:79], v[226:229], v[210:213], v[76:79]
	v_mfma_f32_16x16x32_bf16 v[72:75], v[234:237], v[210:213], v[72:75]
	v_mfma_f32_16x16x32_bf16 v[68:71], v[226:229], v[218:221], v[68:71]
	v_mfma_f32_16x16x32_bf16 v[64:67], v[234:237], v[218:221], v[64:67]
	v_mfma_f32_16x16x32_bf16 v[108:111], v[230:233], v[198:201], v[108:111]
	v_mfma_f32_16x16x32_bf16 v[104:107], v[238:241], v[198:201], v[104:107]
	v_mfma_f32_16x16x32_bf16 v[92:95], v[230:233], v[206:209], v[92:95]
	v_mfma_f32_16x16x32_bf16 v[88:91], v[238:241], v[206:209], v[88:91]
	v_mfma_f32_16x16x32_bf16 v[76:79], v[230:233], v[214:217], v[76:79]
	v_mfma_f32_16x16x32_bf16 v[72:75], v[238:241], v[214:217], v[72:75]
	v_mfma_f32_16x16x32_bf16 v[68:71], v[230:233], v[222:225], v[68:71]
	v_mfma_f32_16x16x32_bf16 v[64:67], v[238:241], v[222:225], v[64:67]
	s_barrier
	ds_read_b128 v[194:197], v154 offset:16384
	ds_read_b128 v[198:201], v154 offset:17408
	ds_read_b128 v[202:205], v154 offset:18432
	ds_read_b128 v[206:209], v154 offset:19456
	ds_read_b128 v[210:213], v154 offset:20480
	ds_read_b128 v[214:217], v154 offset:21504
	ds_read_b128 v[218:221], v154 offset:22528
	ds_read_b128 v[222:225], v154 offset:23552
	global_load_lds_dwordx4 v[246:247], off
	v_lshl_add_u64 v[248:249], s[40:41], 0, v[148:149]
	s_mov_b32 m0, s49
	s_nop 0
	global_load_lds_dwordx4 v[248:249], off
	s_barrier
	s_waitcnt lgkmcnt(0)
	v_mfma_f32_16x16x32_bf16 v[60:63], v[158:161], v[194:197], v[60:63]
	v_mfma_f32_16x16x32_bf16 v[56:59], v[186:189], v[194:197], v[56:59]
	v_mfma_f32_16x16x32_bf16 v[52:55], v[158:161], v[202:205], v[52:55]
	v_mfma_f32_16x16x32_bf16 v[44:47], v[186:189], v[202:205], v[44:47]
	v_mfma_f32_16x16x32_bf16 v[36:39], v[158:161], v[210:213], v[36:39]
	v_mfma_f32_16x16x32_bf16 v[28:31], v[186:189], v[210:213], v[28:31]
	v_mfma_f32_16x16x32_bf16 v[20:23], v[158:161], v[218:221], v[20:23]
	v_mfma_f32_16x16x32_bf16 v[12:15], v[186:189], v[218:221], v[12:15]
	v_mfma_f32_16x16x32_bf16 v[60:63], v[182:185], v[198:201], v[60:63]
	v_mfma_f32_16x16x32_bf16 v[56:59], v[190:193], v[198:201], v[56:59]
	v_mfma_f32_16x16x32_bf16 v[52:55], v[182:185], v[206:209], v[52:55]
	v_mfma_f32_16x16x32_bf16 v[44:47], v[190:193], v[206:209], v[44:47]
	v_mfma_f32_16x16x32_bf16 v[36:39], v[182:185], v[214:217], v[36:39]
	v_mfma_f32_16x16x32_bf16 v[28:31], v[190:193], v[214:217], v[28:31]
	v_mfma_f32_16x16x32_bf16 v[20:23], v[182:185], v[222:225], v[20:23]
	v_mfma_f32_16x16x32_bf16 v[12:15], v[190:193], v[222:225], v[12:15]
	s_barrier
	s_add_u32 s70, s38, 0x80000
	s_addc_u32 s71, s39, 0
	s_add_i32 s21, s69, s43
	s_mov_b32 m0, s21
	s_nop 0
	global_load_lds_dwordx4 v136, s[70:71]
	s_add_i32 m0, s21, 0x2000
	s_nop 0
	global_load_lds_dwordx4 v146, s[70:71]
	s_add_i32 s21, 0, 0x18000
	v_add_u32_e32 v138, s21, v153
	s_waitcnt vmcnt(6)
	s_barrier
; #define PG8_STAGE(bufoff, gbase, v0, v1) do { \
;         __builtin_amdgcn_global_load_lds((const unsigned*)((const char*)(gbase) + (v0)), (LAS unsigned*)(lds + (bufoff) + ldsw), 16, 0, 0); \
;         __builtin_amdgcn_global_load_lds((const unsigned*)((const char*)(gbase) + (v1)), (LAS unsigned*)(lds + (bufoff) + ldsw + 8192), 16, 0, 0); } while (0)
; #define PG8_LDA(dst, b, h) do { _Pragma("unroll") for (int m = 0; m < 4; ++m) _Pragma("unroll") for (int k = 0; k < 2; ++k) dst[m][k] = *(const LAS bf16x8*)(lds + PG8_SA(b, h) + aoff + m * 2048 + k * 1024); } while (0)
; #define PG8_LDB(dst, b, h) do { _Pragma("unroll") for (int n = 0; n < 2; ++n) _Pragma("unroll") for (int k = 0; k < 2; ++k) dst[n][k] = *(const LAS bf16x8*)(lds + PG8_SB(b, h) + boff + n * 2048 + k * 1024); } while (0)
; #define PG8_MMA(ai, bj, At, Bt) do { __builtin_amdgcn_s_setprio(1); _Pragma("unroll") for (int m = 0; m < 4; ++m) _Pragma("unroll") for (int n = 0; n < 2; ++n) _Pragma("unroll") for (int k = 0; k < 2; ++k) \
;         acc[ai][bj][m][n] = __builtin_amdgcn_mfma_f32_16x16x32_bf16(Bt[n][k], At[m][k], acc[ai][bj][m][n], 0, 0, 0); __builtin_amdgcn_s_setprio(0); } while (0)
; #define PG8_WAIT_V(n) asm volatile("s_waitcnt vmcnt(" #n ")" ::: "memory")
; #define PG8_WAIT_L(n) asm volatile("s_waitcnt lgkmcnt(" #n ")" ::: "memory")
; #define PG8_BAR __builtin_amdgcn_s_barrier()
; #define PG8_SCHED __builtin_amdgcn_sched_barrier(0)
; template <class Epi, class Sched>
; __device__ __forceinline__ void gemm_phase(LAS unsigned char* lds, const Sched& S, const Epi& E) {
;     ...
;             PG8_WAIT_V(6); PG8_BAR; PG8_MMA(1, 1, At, B1); PG8_BAR;
;             PG8_LDB(B0, 1, 0); PG8_SCHED; PG8_LDA(At, 1, 0); PG8_STAGE(PG8_SA(0, 1), a2 + xhA, xA0, xA1);
;             PG8_WAIT_L(8); PG8_BAR; PG8_WAIT_L(0); PG8_MMA(0, 0, At, B0); PG8_BAR; PG8_SCHED;
;             PG8_LDB(B1, 1, 1); PG8_STAGE(PG8_SB(1, 0), b3, xB0, xB1);
;             PG8_BAR; PG8_WAIT_L(0); PG8_MMA(0, 1, At, B1); PG8_BAR;
;             PG8_LDA(At, 1, 1); PG8_STAGE(PG8_SA(1, 0), a3, xA0, xA1);
;             PG8_BAR; PG8_WAIT_L(0); PG8_MMA(1, 0, At, B0); PG8_BAR; PG8_SCHED;
	v_mfma_f32_16x16x32_bf16 v[48:51], v[226:229], v[194:197], v[48:51]
	v_mfma_f32_16x16x32_bf16 v[40:43], v[234:237], v[194:197], v[40:43]
	v_mfma_f32_16x16x32_bf16 v[32:35], v[226:229], v[202:205], v[32:35]
	v_mfma_f32_16x16x32_bf16 v[24:27], v[234:237], v[202:205], v[24:27]
	v_mfma_f32_16x16x32_bf16 v[16:19], v[226:229], v[210:213], v[16:19]
	v_mfma_f32_16x16x32_bf16 v[8:11], v[234:237], v[210:213], v[8:11]
	v_mfma_f32_16x16x32_bf16 v[4:7], v[226:229], v[218:221], v[4:7]
	v_mfma_f32_16x16x32_bf16 v[0:3], v[234:237], v[218:221], v[0:3]
	v_mfma_f32_16x16x32_bf16 v[48:51], v[230:233], v[198:201], v[48:51]
	v_mfma_f32_16x16x32_bf16 v[40:43], v[238:241], v[198:201], v[40:43]
	v_mfma_f32_16x16x32_bf16 v[32:35], v[230:233], v[206:209], v[32:35]
	v_mfma_f32_16x16x32_bf16 v[24:27], v[238:241], v[206:209], v[24:27]
	v_mfma_f32_16x16x32_bf16 v[16:19], v[230:233], v[214:217], v[16:19]
	v_mfma_f32_16x16x32_bf16 v[8:11], v[238:241], v[214:217], v[8:11]
	v_mfma_f32_16x16x32_bf16 v[4:7], v[230:233], v[222:225], v[4:7]
	v_mfma_f32_16x16x32_bf16 v[0:3], v[238:241], v[222:225], v[0:3]
	s_barrier
	ds_read_b128 v[158:161], v138
	ds_read_b128 v[182:185], v138 offset:1024
	ds_read_b128 v[186:189], v138 offset:2048
	ds_read_b128 v[190:193], v138 offset:3072
	s_add_u32 s40, s40, 0x80000
	s_addc_u32 s41, s41, 0
	s_mov_b32 m0, s50
	v_lshl_add_u64 v[150:151], s[40:41], 0, v[150:151]
	ds_read_b128 v[194:197], v154 offset:32768
	ds_read_b128 v[198:201], v154 offset:33792
	ds_read_b128 v[202:205], v154 offset:34816
	ds_read_b128 v[206:209], v154 offset:35840
	ds_read_b128 v[210:213], v154 offset:36864
	ds_read_b128 v[214:217], v154 offset:37888
	ds_read_b128 v[218:221], v154 offset:38912
	ds_read_b128 v[222:225], v154 offset:39936
	global_load_lds_dwordx4 v[150:151], off
	v_lshl_add_u64 v[148:149], s[40:41], 0, v[148:149]
	s_mov_b32 m0, s51
	s_nop 0
	global_load_lds_dwordx4 v[148:149], off
	s_waitcnt lgkmcnt(8)
	s_barrier
	s_waitcnt lgkmcnt(0)
	v_mfma_f32_16x16x32_bf16 v[124:127], v[158:161], v[194:197], v[124:127]
	v_mfma_f32_16x16x32_bf16 v[120:123], v[186:189], v[194:197], v[120:123]
	v_mfma_f32_16x16x32_bf16 v[116:119], v[158:161], v[202:205], v[116:119]
	v_mfma_f32_16x16x32_bf16 v[112:115], v[186:189], v[202:205], v[112:115]
	v_mfma_f32_16x16x32_bf16 v[100:103], v[158:161], v[210:213], v[100:103]
	v_mfma_f32_16x16x32_bf16 v[96:99], v[186:189], v[210:213], v[96:99]
	v_mfma_f32_16x16x32_bf16 v[84:87], v[158:161], v[218:221], v[84:87]
	v_mfma_f32_16x16x32_bf16 v[80:83], v[186:189], v[218:221], v[80:83]
	v_mfma_f32_16x16x32_bf16 v[124:127], v[182:185], v[198:201], v[124:127]
	v_mfma_f32_16x16x32_bf16 v[120:123], v[190:193], v[198:201], v[120:123]
	v_mfma_f32_16x16x32_bf16 v[116:119], v[182:185], v[206:209], v[116:119]
	v_mfma_f32_16x16x32_bf16 v[112:115], v[190:193], v[206:209], v[112:115]
	v_mfma_f32_16x16x32_bf16 v[100:103], v[182:185], v[214:217], v[100:103]
	v_mfma_f32_16x16x32_bf16 v[96:99], v[190:193], v[214:217], v[96:99]
	v_mfma_f32_16x16x32_bf16 v[84:87], v[182:185], v[222:225], v[84:87]
	v_mfma_f32_16x16x32_bf16 v[80:83], v[190:193], v[222:225], v[80:83]
	s_barrier
	s_add_i32 s40, 0, 0x1c000
	s_add_i32 s21, s21, s43
	v_add_u32_e32 v138, s40, v153
	v_lshl_add_u64 v[238:239], v[242:243], 0, s[44:45]
	s_mov_b32 m0, s21
	ds_read_b128 v[148:151], v138
	ds_read_b128 v[226:229], v138 offset:1024
	ds_read_b128 v[230:233], v138 offset:2048
	ds_read_b128 v[234:237], v138 offset:3072
	global_load_lds_dwordx4 v[238:239], off
	v_lshl_add_u64 v[238:239], v[244:245], 0, s[44:45]
	s_add_i32 m0, s21, 0x2000
	s_nop 0
	global_load_lds_dwordx4 v[238:239], off
	s_mov_b32 m0, s64
	v_lshl_add_u64 v[238:239], v[246:247], 0, s[44:45]
	s_barrier
; #define PG8_STAGE(bufoff, gbase, v0, v1) do { \
;         __builtin_amdgcn_global_load_lds((const unsigned*)((const char*)(gbase) + (v0)), (LAS unsigned*)(lds + (bufoff) + ldsw), 16, 0, 0); \
;         __builtin_amdgcn_global_load_lds((const unsigned*)((const char*)(gbase) + (v1)), (LAS unsigned*)(lds + (bufoff) + ldsw + 8192), 16, 0, 0); } while (0)
; #define PG8_LDA(dst, b, h) do { _Pragma("unroll") for (int m = 0; m < 4; ++m) _Pragma("unroll") for (int k = 0; k < 2; ++k) dst[m][k] = *(const LAS bf16x8*)(lds + PG8_SA(b, h) + aoff + m * 2048 + k * 1024); } while (0)
; #define PG8_MMA(ai, bj, At, Bt) do { __builtin_amdgcn_s_setprio(1); _Pragma("unroll") for (int m = 0; m < 4; ++m) _Pragma("unroll") for (int n = 0; n < 2; ++n) _Pragma("unroll") for (int k = 0; k < 2; ++k) \
;         acc[ai][bj][m][n] = __builtin_amdgcn_mfma_f32_16x16x32_bf16(Bt[n][k], At[m][k], acc[ai][bj][m][n], 0, 0, 0); __builtin_amdgcn_s_setprio(0); } while (0)
; #define PG8_WAIT_V(n) asm volatile("s_waitcnt vmcnt(" #n ")" ::: "memory")
; #define PG8_WAIT_L(n) asm volatile("s_waitcnt lgkmcnt(" #n ")" ::: "memory")
; #define PG8_BAR __builtin_amdgcn_s_barrier()
; #define PG8_SCHED __builtin_amdgcn_sched_barrier(0)
; template <class Epi, class Sched>
; __device__ __forceinline__ void gemm_phase(LAS unsigned char* lds, const Sched& S, const Epi& E) {
;     ...
;         for (int t = 0; t < nt; t += 2) {
;             const bool last = (t == nt - 2);
;             const char* a1 = cA + (size_t)(t + 1) * kstep;
;             const char* a2 = last ? nA : cA + (size_t)(t + 2) * kstep; const char* b2 = last ? nB : cB + (size_t)(t + 2) * kstep;
;             const char* a3 = a2 + kstep; const char* b3 = b2 + kstep;
;             const unsigned xA0 = last ? nvA0 : vA0, xA1 = last ? nvA1 : vA1, xB0 = last ? nvB0 : vB0, xB1 = last ? nvB1 : vB1;
;             const size_t xhA = last ? nhA : hA, xhB = last ? nhB : hB;
;     ...
;             PG8_BAR; PG8_WAIT_L(0); PG8_MMA(0, 1, At, B1); PG8_BAR;
;             PG8_LDA(At, 1, 1); PG8_STAGE(PG8_SA(1, 0), a3, xA0, xA1);
;             PG8_BAR; PG8_WAIT_L(0); PG8_MMA(1, 0, At, B0); PG8_BAR; PG8_SCHED;
;             PG8_STAGE(PG8_SB(1, 1), b3 + xhB, xB0, xB1);
;             PG8_WAIT_V(6); PG8_BAR; PG8_MMA(1, 1, At, B1); PG8_BAR;
;         }
	s_waitcnt lgkmcnt(0)
	v_mfma_f32_16x16x32_bf16 v[108:111], v[148:151], v[194:197], v[108:111]
	v_mfma_f32_16x16x32_bf16 v[104:107], v[230:233], v[194:197], v[104:107]
	v_mfma_f32_16x16x32_bf16 v[92:95], v[148:151], v[202:205], v[92:95]
	v_mfma_f32_16x16x32_bf16 v[88:91], v[230:233], v[202:205], v[88:91]
	v_mfma_f32_16x16x32_bf16 v[76:79], v[148:151], v[210:213], v[76:79]
	v_mfma_f32_16x16x32_bf16 v[72:75], v[230:233], v[210:213], v[72:75]
	v_mfma_f32_16x16x32_bf16 v[68:71], v[148:151], v[218:221], v[68:71]
	v_mfma_f32_16x16x32_bf16 v[64:67], v[230:233], v[218:221], v[64:67]
	v_mfma_f32_16x16x32_bf16 v[108:111], v[226:229], v[198:201], v[108:111]
	v_mfma_f32_16x16x32_bf16 v[104:107], v[234:237], v[198:201], v[104:107]
	v_mfma_f32_16x16x32_bf16 v[92:95], v[226:229], v[206:209], v[92:95]
	v_mfma_f32_16x16x32_bf16 v[88:91], v[234:237], v[206:209], v[88:91]
	v_mfma_f32_16x16x32_bf16 v[76:79], v[226:229], v[214:217], v[76:79]
	v_mfma_f32_16x16x32_bf16 v[72:75], v[234:237], v[214:217], v[72:75]
	v_mfma_f32_16x16x32_bf16 v[68:71], v[226:229], v[222:225], v[68:71]
	v_mfma_f32_16x16x32_bf16 v[64:67], v[234:237], v[222:225], v[64:67]
	s_barrier
	ds_read_b128 v[194:197], v154 offset:49152
	ds_read_b128 v[198:201], v154 offset:50176
	ds_read_b128 v[202:205], v154 offset:51200
	ds_read_b128 v[206:209], v154 offset:52224
	ds_read_b128 v[210:213], v154 offset:53248
	ds_read_b128 v[214:217], v154 offset:54272
	ds_read_b128 v[218:221], v154 offset:55296
	ds_read_b128 v[222:225], v154 offset:56320
	global_load_lds_dwordx4 v[238:239], off
	v_lshl_add_u64 v[238:239], v[248:249], 0, s[44:45]
	s_mov_b32 m0, s65
	s_nop 0
	global_load_lds_dwordx4 v[238:239], off
	s_barrier
	s_waitcnt lgkmcnt(0)
	v_mfma_f32_16x16x32_bf16 v[60:63], v[158:161], v[194:197], v[60:63]
	v_mfma_f32_16x16x32_bf16 v[56:59], v[186:189], v[194:197], v[56:59]
	v_mfma_f32_16x16x32_bf16 v[52:55], v[158:161], v[202:205], v[52:55]
	v_mfma_f32_16x16x32_bf16 v[44:47], v[186:189], v[202:205], v[44:47]
	v_mfma_f32_16x16x32_bf16 v[36:39], v[158:161], v[210:213], v[36:39]
	v_mfma_f32_16x16x32_bf16 v[28:31], v[186:189], v[210:213], v[28:31]
	v_mfma_f32_16x16x32_bf16 v[20:23], v[158:161], v[218:221], v[20:23]
	v_mfma_f32_16x16x32_bf16 v[12:15], v[186:189], v[218:221], v[12:15]
	v_mfma_f32_16x16x32_bf16 v[60:63], v[182:185], v[198:201], v[60:63]
	v_mfma_f32_16x16x32_bf16 v[56:59], v[190:193], v[198:201], v[56:59]
	v_mfma_f32_16x16x32_bf16 v[52:55], v[182:185], v[206:209], v[52:55]
	v_mfma_f32_16x16x32_bf16 v[44:47], v[190:193], v[206:209], v[44:47]
	v_mfma_f32_16x16x32_bf16 v[36:39], v[182:185], v[214:217], v[36:39]
	v_mfma_f32_16x16x32_bf16 v[28:31], v[190:193], v[214:217], v[28:31]
	v_mfma_f32_16x16x32_bf16 v[20:23], v[182:185], v[222:225], v[20:23]
	v_mfma_f32_16x16x32_bf16 v[12:15], v[190:193], v[222:225], v[12:15]
	s_barrier
	s_add_u32 s38, s38, 0x80080
	s_addc_u32 s39, s39, 0
	s_add_i32 s21, s40, s43
	s_mov_b32 m0, s21
	s_nop 0
	global_load_lds_dwordx4 v136, s[38:39]
	s_add_i32 m0, s21, 0x2000
	s_nop 0
	global_load_lds_dwordx4 v146, s[38:39]
	s_waitcnt vmcnt(6)
	s_barrier
	v_mfma_f32_16x16x32_bf16 v[48:51], v[148:151], v[194:197], v[48:51]
	v_mfma_f32_16x16x32_bf16 v[40:43], v[230:233], v[194:197], v[40:43]
	v_mfma_f32_16x16x32_bf16 v[32:35], v[148:151], v[202:205], v[32:35]
	v_mfma_f32_16x16x32_bf16 v[24:27], v[230:233], v[202:205], v[24:27]
	v_mfma_f32_16x16x32_bf16 v[16:19], v[148:151], v[210:213], v[16:19]
	v_mfma_f32_16x16x32_bf16 v[8:11], v[230:233], v[210:213], v[8:11]
	v_mfma_f32_16x16x32_bf16 v[4:7], v[148:151], v[218:221], v[4:7]
	v_mfma_f32_16x16x32_bf16 v[0:3], v[230:233], v[218:221], v[0:3]
	v_mfma_f32_16x16x32_bf16 v[48:51], v[226:229], v[198:201], v[48:51]
	v_mfma_f32_16x16x32_bf16 v[40:43], v[234:237], v[198:201], v[40:43]
	v_mfma_f32_16x16x32_bf16 v[32:35], v[226:229], v[206:209], v[32:35]
	v_mfma_f32_16x16x32_bf16 v[24:27], v[234:237], v[206:209], v[24:27]
	v_mfma_f32_16x16x32_bf16 v[16:19], v[226:229], v[214:217], v[16:19]
	v_mfma_f32_16x16x32_bf16 v[8:11], v[234:237], v[214:217], v[8:11]
	v_mfma_f32_16x16x32_bf16 v[4:7], v[226:229], v[222:225], v[4:7]
	v_mfma_f32_16x16x32_bf16 v[0:3], v[234:237], v[222:225], v[0:3]
	s_add_i32 s15, s15, 2
	s_add_u32 s26, s26, 0x100
	s_addc_u32 s27, s27, 0
	s_add_u32 s34, s34, 0x100
	s_addc_u32 s35, s35, 0
	s_cmp_gt_u32 s15, 29
	s_cbranch_scc1 .Lrot_exit_0
	s_cmp_eq_u32 s15, 28
	s_cselect_b64 s[40:41], -1, 0
	s_and_b64 vcc, exec, s[40:41]
	v_mov_b64_e32 v[148:149], v[130:131]
	v_mov_b64_e32 v[150:151], v[128:129]
	v_mov_b32_e32 v146, v156
	v_mov_b32_e32 v136, v155
	s_mov_b64 s[38:39], s[24:25]
	s_cbranch_vccnz .Lrot_join_0
	v_mov_b64_e32 v[148:149], v[134:135]
	v_mov_b64_e32 v[150:151], v[132:133]
	v_mov_b32_e32 v146, v142
	v_mov_b32_e32 v136, v144
	s_mov_b64 s[38:39], s[34:35]

; #define PG8_STAGE(bufoff, gbase, v0, v1) do { \
;         __builtin_amdgcn_global_load_lds((const unsigned*)((const char*)(gbase) + (v0)), (LAS unsigned*)(lds + (bufoff) + ldsw), 16, 0, 0); \
;         __builtin_amdgcn_global_load_lds((const unsigned*)((const char*)(gbase) + (v1)), (LAS unsigned*)(lds + (bufoff) + ldsw + 8192), 16, 0, 0); } while (0)
; #define PG8_LDA(dst, b, h) do { _Pragma("unroll") for (int m = 0; m < 4; ++m) _Pragma("unroll") for (int k = 0; k < 2; ++k) dst[m][k] = *(const LAS bf16x8*)(lds + PG8_SA(b, h) + aoff + m * 2048 + k * 1024); } while (0)
; #define PG8_LDB(dst, b, h) do { _Pragma("unroll") for (int n = 0; n < 2; ++n) _Pragma("unroll") for (int k = 0; k < 2; ++k) dst[n][k] = *(const LAS bf16x8*)(lds + PG8_SB(b, h) + boff + n * 2048 + k * 1024); } while (0)
; #define PG8_MMA(ai, bj, At, Bt) do { __builtin_amdgcn_s_setprio(1); _Pragma("unroll") for (int m = 0; m < 4; ++m) _Pragma("unroll") for (int n = 0; n < 2; ++n) _Pragma("unroll") for (int k = 0; k < 2; ++k) \
;         acc[ai][bj][m][n] = __builtin_amdgcn_mfma_f32_16x16x32_bf16(Bt[n][k], At[m][k], acc[ai][bj][m][n], 0, 0, 0); __builtin_amdgcn_s_setprio(0); } while (0)
; #define PG8_WAIT_V(n) asm volatile("s_waitcnt vmcnt(" #n ")" ::: "memory")
; #define PG8_WAIT_L(n) asm volatile("s_waitcnt lgkmcnt(" #n ")" ::: "memory")
; #define PG8_BAR __builtin_amdgcn_s_barrier()
; #define PG8_SCHED __builtin_amdgcn_sched_barrier(0)
; template <class Epi, class Sched>
; __device__ __forceinline__ void gemm_phase(LAS unsigned char* lds, const Sched& S, const Epi& E) {
;     ...
;             PG8_LDB(B0, 0, 0); PG8_SCHED; PG8_LDA(At, 0, 0); PG8_STAGE(PG8_SA(1, 1), a1 + hA, vA0, vA1);
;             PG8_WAIT_L(8); PG8_BAR; PG8_WAIT_L(0); PG8_MMA(0, 0, At, B0); PG8_BAR; PG8_SCHED;
;             PG8_LDB(B1, 0, 1); PG8_STAGE(PG8_SB(0, 0), b2, xB0, xB1);
;             PG8_BAR; PG8_WAIT_L(0); PG8_MMA(0, 1, At, B1); PG8_BAR;
;             PG8_LDA(At, 0, 1); PG8_STAGE(PG8_SA(0, 0), a2, xA0, xA1);
;             PG8_BAR; PG8_WAIT_L(0); PG8_MMA(1, 0, At, B0); PG8_BAR; PG8_SCHED;
;             PG8_STAGE(PG8_SB(0, 1), b2 + xhB, xB0, xB1);
;             PG8_WAIT_V(6); PG8_BAR; PG8_MMA(1, 1, At, B1); PG8_BAR;
.Lrot_body_1:
	ds_read_b128 v[158:161], v138
	ds_read_b128 v[186:189], v138 offset:1024
	ds_read_b128 v[190:193], v138 offset:2048
	ds_read_b128 v[194:197], v138 offset:3072
	v_lshl_add_u64 v[230:231], s[34:35], 0, v[134:135]
	s_add_i32 m0, s91, 0xc000
	ds_read_b128 v[198:201], v185
	ds_read_b128 v[202:205], v185 offset:1024
	ds_read_b128 v[206:209], v185 offset:2048
	ds_read_b128 v[210:213], v185 offset:3072
	ds_read_b128 v[214:217], v185 offset:4096
	ds_read_b128 v[218:221], v185 offset:5120
	ds_read_b128 v[222:225], v185 offset:6144
	ds_read_b128 v[226:229], v185 offset:7168
	global_load_lds_dwordx4 v[230:231], off
	v_lshl_add_u64 v[230:231], s[34:35], 0, v[150:151]
	s_add_i32 m0, s91, 0xe000
	s_nop 0
	global_load_lds_dwordx4 v[230:231], off
	s_waitcnt lgkmcnt(8)
	s_barrier
	s_waitcnt lgkmcnt(0)
	v_mfma_f32_16x16x32_bf16 v[124:127], v[158:161], v[198:201], v[124:127]
	v_mfma_f32_16x16x32_bf16 v[120:123], v[190:193], v[198:201], v[120:123]
	v_mfma_f32_16x16x32_bf16 v[116:119], v[158:161], v[206:209], v[116:119]
	v_mfma_f32_16x16x32_bf16 v[112:115], v[190:193], v[206:209], v[112:115]
	v_mfma_f32_16x16x32_bf16 v[108:111], v[158:161], v[214:217], v[108:111]
	v_mfma_f32_16x16x32_bf16 v[104:107], v[190:193], v[214:217], v[104:107]
	v_mfma_f32_16x16x32_bf16 v[100:103], v[158:161], v[222:225], v[100:103]
	v_mfma_f32_16x16x32_bf16 v[96:99], v[190:193], v[222:225], v[96:99]
	v_mfma_f32_16x16x32_bf16 v[124:127], v[186:189], v[202:205], v[124:127]
	v_mfma_f32_16x16x32_bf16 v[120:123], v[194:197], v[202:205], v[120:123]
	v_mfma_f32_16x16x32_bf16 v[116:119], v[186:189], v[210:213], v[116:119]
	v_mfma_f32_16x16x32_bf16 v[112:115], v[194:197], v[210:213], v[112:115]
	v_mfma_f32_16x16x32_bf16 v[108:111], v[186:189], v[218:221], v[108:111]
	v_mfma_f32_16x16x32_bf16 v[104:107], v[194:197], v[218:221], v[104:107]
	v_mfma_f32_16x16x32_bf16 v[100:103], v[186:189], v[226:229], v[100:103]
	v_mfma_f32_16x16x32_bf16 v[96:99], v[194:197], v[226:229], v[96:99]
	s_barrier
	s_add_i32 vcc_lo, 0, 0x14000
	s_add_i32 s65, s65, s9
	v_add_u32_e32 v138, vcc_lo, v184
	s_mov_b32 m0, s65
	ds_read_b128 v[230:233], v138
	ds_read_b128 v[234:237], v138 offset:1024
	ds_read_b128 v[238:241], v138 offset:2048
	ds_read_b128 v[242:245], v138 offset:3072
	global_load_lds_dwordx4 v136, s[92:93]
	s_add_i32 m0, s65, 0x2000
	v_mov_b32_e32 v157, v137
	global_load_lds_dwordx4 v156, s[92:93]
	v_lshl_add_u64 v[246:247], s[92:93], 0, v[136:137]
	v_lshl_add_u64 v[248:249], s[92:93], 0, v[156:157]
	s_mov_b32 m0, s91
	v_lshl_add_u64 v[250:251], s[54:55], 0, v[154:155]
	s_barrier
	s_waitcnt lgkmcnt(0)
	v_mfma_f32_16x16x32_bf16 v[92:95], v[230:233], v[198:201], v[92:95]
	v_mfma_f32_16x16x32_bf16 v[88:91], v[238:241], v[198:201], v[88:91]
	v_mfma_f32_16x16x32_bf16 v[84:87], v[230:233], v[206:209], v[84:87]
	v_mfma_f32_16x16x32_bf16 v[80:83], v[238:241], v[206:209], v[80:83]
	v_mfma_f32_16x16x32_bf16 v[76:79], v[230:233], v[214:217], v[76:79]
	v_mfma_f32_16x16x32_bf16 v[72:75], v[238:241], v[214:217], v[72:75]
	v_mfma_f32_16x16x32_bf16 v[68:71], v[230:233], v[222:225], v[68:71]
	v_mfma_f32_16x16x32_bf16 v[64:67], v[238:241], v[222:225], v[64:67]
	v_mfma_f32_16x16x32_bf16 v[92:95], v[234:237], v[202:205], v[92:95]
	v_mfma_f32_16x16x32_bf16 v[88:91], v[242:245], v[202:205], v[88:91]
	v_mfma_f32_16x16x32_bf16 v[84:87], v[234:237], v[210:213], v[84:87]
	v_mfma_f32_16x16x32_bf16 v[80:83], v[242:245], v[210:213], v[80:83]
	v_mfma_f32_16x16x32_bf16 v[76:79], v[234:237], v[218:221], v[76:79]
	v_mfma_f32_16x16x32_bf16 v[72:75], v[242:245], v[218:221], v[72:75]
	v_mfma_f32_16x16x32_bf16 v[68:71], v[234:237], v[226:229], v[68:71]
	v_mfma_f32_16x16x32_bf16 v[64:67], v[242:245], v[226:229], v[64:67]
	s_barrier
	ds_read_b128 v[198:201], v185 offset:16384
	ds_read_b128 v[202:205], v185 offset:17408
	ds_read_b128 v[206:209], v185 offset:18432
	ds_read_b128 v[210:213], v185 offset:19456
	ds_read_b128 v[214:217], v185 offset:20480
	ds_read_b128 v[218:221], v185 offset:21504
	ds_read_b128 v[222:225], v185 offset:22528
	ds_read_b128 v[226:229], v185 offset:23552
	global_load_lds_dwordx4 v[250:251], off
	v_lshl_add_u64 v[140:141], s[54:55], 0, v[152:153]
	s_mov_b32 m0, s50
	s_nop 0
	global_load_lds_dwordx4 v[140:141], off
	s_barrier
	s_waitcnt lgkmcnt(0)
	v_mfma_f32_16x16x32_bf16 v[60:63], v[158:161], v[198:201], v[60:63]
	v_mfma_f32_16x16x32_bf16 v[56:59], v[190:193], v[198:201], v[56:59]
	v_mfma_f32_16x16x32_bf16 v[52:55], v[158:161], v[206:209], v[52:55]
	v_mfma_f32_16x16x32_bf16 v[48:51], v[190:193], v[206:209], v[48:51]
	v_mfma_f32_16x16x32_bf16 v[44:47], v[158:161], v[214:217], v[44:47]
	v_mfma_f32_16x16x32_bf16 v[40:43], v[190:193], v[214:217], v[40:43]
	v_mfma_f32_16x16x32_bf16 v[36:39], v[158:161], v[222:225], v[36:39]
	v_mfma_f32_16x16x32_bf16 v[32:35], v[190:193], v[222:225], v[32:35]
	v_mfma_f32_16x16x32_bf16 v[60:63], v[186:189], v[202:205], v[60:63]
	v_mfma_f32_16x16x32_bf16 v[56:59], v[194:197], v[202:205], v[56:59]
	v_mfma_f32_16x16x32_bf16 v[52:55], v[186:189], v[210:213], v[52:55]
	v_mfma_f32_16x16x32_bf16 v[48:51], v[194:197], v[210:213], v[48:51]
	v_mfma_f32_16x16x32_bf16 v[44:47], v[186:189], v[218:221], v[44:47]
	v_mfma_f32_16x16x32_bf16 v[40:43], v[194:197], v[218:221], v[40:43]
	v_mfma_f32_16x16x32_bf16 v[36:39], v[186:189], v[226:229], v[36:39]
	v_mfma_f32_16x16x32_bf16 v[32:35], v[194:197], v[226:229], v[32:35]
	s_barrier
	s_add_u32 s88, s92, s88
	s_addc_u32 s89, s93, s89
	s_add_i32 s65, vcc_lo, s9
	s_mov_b32 m0, s65
	v_lshl_add_u64 v[160:161], s[88:89], 0, v[136:137]
	global_load_lds_dwordx4 v136, s[88:89]
	s_add_i32 m0, s65, 0x2000
	v_lshl_add_u64 v[138:139], s[88:89], 0, v[156:157]
	global_load_lds_dwordx4 v156, s[88:89]
	s_add_i32 s65, 0, 0x18000
	v_add_u32_e32 v136, s65, v184
	s_waitcnt vmcnt(6)
	s_barrier
; #define PG8_STAGE(bufoff, gbase, v0, v1) do { \
;         __builtin_amdgcn_global_load_lds((const unsigned*)((const char*)(gbase) + (v0)), (LAS unsigned*)(lds + (bufoff) + ldsw), 16, 0, 0); \
;         __builtin_amdgcn_global_load_lds((const unsigned*)((const char*)(gbase) + (v1)), (LAS unsigned*)(lds + (bufoff) + ldsw + 8192), 16, 0, 0); } while (0)
; #define PG8_LDA(dst, b, h) do { _Pragma("unroll") for (int m = 0; m < 4; ++m) _Pragma("unroll") for (int k = 0; k < 2; ++k) dst[m][k] = *(const LAS bf16x8*)(lds + PG8_SA(b, h) + aoff + m * 2048 + k * 1024); } while (0)
; #define PG8_LDB(dst, b, h) do { _Pragma("unroll") for (int n = 0; n < 2; ++n) _Pragma("unroll") for (int k = 0; k < 2; ++k) dst[n][k] = *(const LAS bf16x8*)(lds + PG8_SB(b, h) + boff + n * 2048 + k * 1024); } while (0)
; #define PG8_MMA(ai, bj, At, Bt) do { __builtin_amdgcn_s_setprio(1); _Pragma("unroll") for (int m = 0; m < 4; ++m) _Pragma("unroll") for (int n = 0; n < 2; ++n) _Pragma("unroll") for (int k = 0; k < 2; ++k) \
;         acc[ai][bj][m][n] = __builtin_amdgcn_mfma_f32_16x16x32_bf16(Bt[n][k], At[m][k], acc[ai][bj][m][n], 0, 0, 0); __builtin_amdgcn_s_setprio(0); } while (0)
; #define PG8_WAIT_V(n) asm volatile("s_waitcnt vmcnt(" #n ")" ::: "memory")
; #define PG8_WAIT_L(n) asm volatile("s_waitcnt lgkmcnt(" #n ")" ::: "memory")
; #define PG8_BAR __builtin_amdgcn_s_barrier()
; #define PG8_SCHED __builtin_amdgcn_sched_barrier(0)
; template <class Epi, class Sched>
; __device__ __forceinline__ void gemm_phase(LAS unsigned char* lds, const Sched& S, const Epi& E) {
;     ...
;             PG8_WAIT_V(6); PG8_BAR; PG8_MMA(1, 1, At, B1); PG8_BAR;
;             PG8_LDB(B0, 1, 0); PG8_SCHED; PG8_LDA(At, 1, 0); PG8_STAGE(PG8_SA(0, 1), a2 + xhA, xA0, xA1);
;             PG8_WAIT_L(8); PG8_BAR; PG8_WAIT_L(0); PG8_MMA(0, 0, At, B0); PG8_BAR; PG8_SCHED;
;             PG8_LDB(B1, 1, 1); PG8_STAGE(PG8_SB(1, 0), b3, xB0, xB1);
;             PG8_BAR; PG8_WAIT_L(0); PG8_MMA(0, 1, At, B1); PG8_BAR;
;             PG8_LDA(At, 1, 1); PG8_STAGE(PG8_SA(1, 0), a3, xA0, xA1);
;             PG8_BAR; PG8_WAIT_L(0); PG8_MMA(1, 0, At, B0); PG8_BAR; PG8_SCHED;
;             PG8_STAGE(PG8_SB(1, 1), b3 + xhB, xB0, xB1);
	v_mfma_f32_16x16x32_bf16 v[28:31], v[230:233], v[198:201], v[28:31]
	v_mfma_f32_16x16x32_bf16 v[24:27], v[238:241], v[198:201], v[24:27]
	v_mfma_f32_16x16x32_bf16 v[20:23], v[230:233], v[206:209], v[20:23]
	v_mfma_f32_16x16x32_bf16 v[16:19], v[238:241], v[206:209], v[16:19]
	v_mfma_f32_16x16x32_bf16 v[12:15], v[230:233], v[214:217], v[12:15]
	v_mfma_f32_16x16x32_bf16 v[8:11], v[238:241], v[214:217], v[8:11]
	v_mfma_f32_16x16x32_bf16 v[4:7], v[230:233], v[222:225], v[4:7]
	v_mfma_f32_16x16x32_bf16 v[0:3], v[238:241], v[222:225], v[0:3]
	v_mfma_f32_16x16x32_bf16 v[28:31], v[234:237], v[202:205], v[28:31]
	v_mfma_f32_16x16x32_bf16 v[24:27], v[242:245], v[202:205], v[24:27]
	v_mfma_f32_16x16x32_bf16 v[20:23], v[234:237], v[210:213], v[20:23]
	v_mfma_f32_16x16x32_bf16 v[16:19], v[242:245], v[210:213], v[16:19]
	v_mfma_f32_16x16x32_bf16 v[12:15], v[234:237], v[218:221], v[12:15]
	v_mfma_f32_16x16x32_bf16 v[8:11], v[242:245], v[218:221], v[8:11]
	v_mfma_f32_16x16x32_bf16 v[4:7], v[234:237], v[226:229], v[4:7]
	v_mfma_f32_16x16x32_bf16 v[0:3], v[242:245], v[226:229], v[0:3]
	s_barrier
	ds_read_b128 v[156:159], v136
	ds_read_b128 v[186:189], v136 offset:1024
	ds_read_b128 v[190:193], v136 offset:2048
	ds_read_b128 v[194:197], v136 offset:3072
	s_add_u32 s54, s54, s82
	s_addc_u32 s55, s55, s83
	s_mov_b32 m0, s51
	v_lshl_add_u64 v[154:155], s[54:55], 0, v[154:155]
	ds_read_b128 v[198:201], v185 offset:32768
	ds_read_b128 v[202:205], v185 offset:33792
	ds_read_b128 v[206:209], v185 offset:34816
	ds_read_b128 v[210:213], v185 offset:35840
	ds_read_b128 v[214:217], v185 offset:36864
	ds_read_b128 v[218:221], v185 offset:37888
	ds_read_b128 v[222:225], v185 offset:38912
	ds_read_b128 v[226:229], v185 offset:39936
	global_load_lds_dwordx4 v[154:155], off
	v_lshl_add_u64 v[152:153], s[54:55], 0, v[152:153]
	s_mov_b32 m0, s8
	s_nop 0
	global_load_lds_dwordx4 v[152:153], off
	s_waitcnt lgkmcnt(8)
	s_barrier
	s_waitcnt lgkmcnt(0)
	v_mfma_f32_16x16x32_bf16 v[124:127], v[156:159], v[198:201], v[124:127]
	v_mfma_f32_16x16x32_bf16 v[120:123], v[190:193], v[198:201], v[120:123]
	v_mfma_f32_16x16x32_bf16 v[116:119], v[156:159], v[206:209], v[116:119]
	v_mfma_f32_16x16x32_bf16 v[112:115], v[190:193], v[206:209], v[112:115]
	v_mfma_f32_16x16x32_bf16 v[108:111], v[156:159], v[214:217], v[108:111]
	v_mfma_f32_16x16x32_bf16 v[104:107], v[190:193], v[214:217], v[104:107]
	v_mfma_f32_16x16x32_bf16 v[100:103], v[156:159], v[222:225], v[100:103]
	v_mfma_f32_16x16x32_bf16 v[96:99], v[190:193], v[222:225], v[96:99]
	v_mfma_f32_16x16x32_bf16 v[124:127], v[186:189], v[202:205], v[124:127]
	v_mfma_f32_16x16x32_bf16 v[120:123], v[194:197], v[202:205], v[120:123]
	v_mfma_f32_16x16x32_bf16 v[116:119], v[186:189], v[210:213], v[116:119]
	v_mfma_f32_16x16x32_bf16 v[112:115], v[194:197], v[210:213], v[112:115]
	v_mfma_f32_16x16x32_bf16 v[108:111], v[186:189], v[218:221], v[108:111]
	v_mfma_f32_16x16x32_bf16 v[104:107], v[194:197], v[218:221], v[104:107]
	v_mfma_f32_16x16x32_bf16 v[100:103], v[186:189], v[226:229], v[100:103]
	v_mfma_f32_16x16x32_bf16 v[96:99], v[194:197], v[226:229], v[96:99]
	s_barrier
	s_add_i32 s54, 0, 0x1c000
	s_add_i32 s55, s65, s9
	v_add_u32_e32 v136, s54, v184
	v_lshl_add_u64 v[242:243], v[246:247], 0, s[44:45]
	s_mov_b32 m0, s55
	ds_read_b128 v[152:155], v136
	ds_read_b128 v[230:233], v136 offset:1024
	ds_read_b128 v[234:237], v136 offset:2048
	ds_read_b128 v[238:241], v136 offset:3072
	global_load_lds_dwordx4 v[242:243], off
	v_lshl_add_u64 v[242:243], v[248:249], 0, s[44:45]
	s_add_i32 m0, s55, 0x2000
	s_nop 0
	global_load_lds_dwordx4 v[242:243], off
	s_mov_b32 m0, s21
	v_lshl_add_u64 v[242:243], v[250:251], 0, s[44:45]
	s_barrier
	s_waitcnt lgkmcnt(0)
	v_mfma_f32_16x16x32_bf16 v[92:95], v[152:155], v[198:201], v[92:95]
	v_mfma_f32_16x16x32_bf16 v[88:91], v[234:237], v[198:201], v[88:91]
	v_mfma_f32_16x16x32_bf16 v[84:87], v[152:155], v[206:209], v[84:87]
	v_mfma_f32_16x16x32_bf16 v[80:83], v[234:237], v[206:209], v[80:83]
	v_mfma_f32_16x16x32_bf16 v[76:79], v[152:155], v[214:217], v[76:79]
	v_mfma_f32_16x16x32_bf16 v[72:75], v[234:237], v[214:217], v[72:75]
	v_mfma_f32_16x16x32_bf16 v[68:71], v[152:155], v[222:225], v[68:71]
	v_mfma_f32_16x16x32_bf16 v[64:67], v[234:237], v[222:225], v[64:67]
	v_mfma_f32_16x16x32_bf16 v[92:95], v[230:233], v[202:205], v[92:95]
	v_mfma_f32_16x16x32_bf16 v[88:91], v[238:241], v[202:205], v[88:91]
	v_mfma_f32_16x16x32_bf16 v[84:87], v[230:233], v[210:213], v[84:87]
	v_mfma_f32_16x16x32_bf16 v[80:83], v[238:241], v[210:213], v[80:83]
	v_mfma_f32_16x16x32_bf16 v[76:79], v[230:233], v[218:221], v[76:79]
	v_mfma_f32_16x16x32_bf16 v[72:75], v[238:241], v[218:221], v[72:75]
	v_mfma_f32_16x16x32_bf16 v[68:71], v[230:233], v[226:229], v[68:71]
	v_mfma_f32_16x16x32_bf16 v[64:67], v[238:241], v[226:229], v[64:67]
	s_barrier
; #define PG8_STAGE(bufoff, gbase, v0, v1) do { \
;         __builtin_amdgcn_global_load_lds((const unsigned*)((const char*)(gbase) + (v0)), (LAS unsigned*)(lds + (bufoff) + ldsw), 16, 0, 0); \
;         __builtin_amdgcn_global_load_lds((const unsigned*)((const char*)(gbase) + (v1)), (LAS unsigned*)(lds + (bufoff) + ldsw + 8192), 16, 0, 0); } while (0)
; #define PG8_LDA(dst, b, h) do { _Pragma("unroll") for (int m = 0; m < 4; ++m) _Pragma("unroll") for (int k = 0; k < 2; ++k) dst[m][k] = *(const LAS bf16x8*)(lds + PG8_SA(b, h) + aoff + m * 2048 + k * 1024); } while (0)
; #define PG8_MMA(ai, bj, At, Bt) do { __builtin_amdgcn_s_setprio(1); _Pragma("unroll") for (int m = 0; m < 4; ++m) _Pragma("unroll") for (int n = 0; n < 2; ++n) _Pragma("unroll") for (int k = 0; k < 2; ++k) \
;         acc[ai][bj][m][n] = __builtin_amdgcn_mfma_f32_16x16x32_bf16(Bt[n][k], At[m][k], acc[ai][bj][m][n], 0, 0, 0); __builtin_amdgcn_s_setprio(0); } while (0)
; #define PG8_WAIT_V(n) asm volatile("s_waitcnt vmcnt(" #n ")" ::: "memory")
; #define PG8_WAIT_L(n) asm volatile("s_waitcnt lgkmcnt(" #n ")" ::: "memory")
; #define PG8_BAR __builtin_amdgcn_s_barrier()
; #define PG8_SCHED __builtin_amdgcn_sched_barrier(0)
; template <class Epi, class Sched>
; __device__ __forceinline__ void gemm_phase(LAS unsigned char* lds, const Sched& S, const Epi& E) {
;     ...
;         for (int t = 0; t < nt; t += 2) {
;             const bool last = (t == nt - 2);
;             const char* a1 = cA + (size_t)(t + 1) * kstep;
;             const char* a2 = last ? nA : cA + (size_t)(t + 2) * kstep; const char* b2 = last ? nB : cB + (size_t)(t + 2) * kstep;
;             const char* a3 = a2 + kstep; const char* b3 = b2 + kstep;
;             const unsigned xA0 = last ? nvA0 : vA0, xA1 = last ? nvA1 : vA1, xB0 = last ? nvB0 : vB0, xB1 = last ? nvB1 : vB1;
;             const size_t xhA = last ? nhA : hA, xhB = last ? nhB : hB;
;     ...
;             PG8_LDA(At, 1, 1); PG8_STAGE(PG8_SA(1, 0), a3, xA0, xA1);
;             PG8_BAR; PG8_WAIT_L(0); PG8_MMA(1, 0, At, B0); PG8_BAR; PG8_SCHED;
;             PG8_STAGE(PG8_SB(1, 1), b3 + xhB, xB0, xB1);
;             PG8_WAIT_V(6); PG8_BAR; PG8_MMA(1, 1, At, B1); PG8_BAR;
;         }
	ds_read_b128 v[198:201], v185 offset:49152
	ds_read_b128 v[202:205], v185 offset:50176
	ds_read_b128 v[206:209], v185 offset:51200
	ds_read_b128 v[210:213], v185 offset:52224
	ds_read_b128 v[214:217], v185 offset:53248
	ds_read_b128 v[218:221], v185 offset:54272
	ds_read_b128 v[222:225], v185 offset:55296
	ds_read_b128 v[226:229], v185 offset:56320
	global_load_lds_dwordx4 v[242:243], off
	v_lshl_add_u64 v[140:141], v[140:141], 0, s[44:45]
	s_mov_b32 m0, s24
	s_nop 0
	global_load_lds_dwordx4 v[140:141], off
	s_barrier
	s_waitcnt lgkmcnt(0)
	v_mfma_f32_16x16x32_bf16 v[60:63], v[156:159], v[198:201], v[60:63]
	v_mfma_f32_16x16x32_bf16 v[56:59], v[190:193], v[198:201], v[56:59]
	v_mfma_f32_16x16x32_bf16 v[52:55], v[156:159], v[206:209], v[52:55]
	v_mfma_f32_16x16x32_bf16 v[48:51], v[190:193], v[206:209], v[48:51]
	v_mfma_f32_16x16x32_bf16 v[44:47], v[156:159], v[214:217], v[44:47]
	v_mfma_f32_16x16x32_bf16 v[40:43], v[190:193], v[214:217], v[40:43]
	v_mfma_f32_16x16x32_bf16 v[36:39], v[156:159], v[222:225], v[36:39]
	v_mfma_f32_16x16x32_bf16 v[32:35], v[190:193], v[222:225], v[32:35]
	v_mfma_f32_16x16x32_bf16 v[60:63], v[186:189], v[202:205], v[60:63]
	v_mfma_f32_16x16x32_bf16 v[56:59], v[194:197], v[202:205], v[56:59]
	v_mfma_f32_16x16x32_bf16 v[52:55], v[186:189], v[210:213], v[52:55]
	v_mfma_f32_16x16x32_bf16 v[48:51], v[194:197], v[210:213], v[48:51]
	v_mfma_f32_16x16x32_bf16 v[44:47], v[186:189], v[218:221], v[44:47]
	v_mfma_f32_16x16x32_bf16 v[40:43], v[194:197], v[218:221], v[40:43]
	v_mfma_f32_16x16x32_bf16 v[36:39], v[186:189], v[226:229], v[36:39]
	v_mfma_f32_16x16x32_bf16 v[32:35], v[194:197], v[226:229], v[32:35]
	s_barrier
	s_add_i32 s54, s54, s9
	v_lshl_add_u64 v[140:141], v[160:161], 0, s[44:45]
	s_mov_b32 m0, s54
	v_lshl_add_u64 v[138:139], v[138:139], 0, s[44:45]
	global_load_lds_dwordx4 v[140:141], off
	s_add_i32 m0, s54, 0x2000
	s_nop 0
	global_load_lds_dwordx4 v[138:139], off
	s_waitcnt vmcnt(6)
	s_barrier
	v_mfma_f32_16x16x32_bf16 v[28:31], v[152:155], v[198:201], v[28:31]
	v_mfma_f32_16x16x32_bf16 v[24:27], v[234:237], v[198:201], v[24:27]
	v_mfma_f32_16x16x32_bf16 v[20:23], v[152:155], v[206:209], v[20:23]
	v_mfma_f32_16x16x32_bf16 v[16:19], v[234:237], v[206:209], v[16:19]
	v_mfma_f32_16x16x32_bf16 v[12:15], v[152:155], v[214:217], v[12:15]
	v_mfma_f32_16x16x32_bf16 v[8:11], v[234:237], v[214:217], v[8:11]
	v_mfma_f32_16x16x32_bf16 v[4:7], v[152:155], v[222:225], v[4:7]
	v_mfma_f32_16x16x32_bf16 v[0:3], v[234:237], v[222:225], v[0:3]
	v_mfma_f32_16x16x32_bf16 v[28:31], v[230:233], v[202:205], v[28:31]
	v_mfma_f32_16x16x32_bf16 v[24:27], v[238:241], v[202:205], v[24:27]
	v_mfma_f32_16x16x32_bf16 v[20:23], v[230:233], v[210:213], v[20:23]
	v_mfma_f32_16x16x32_bf16 v[16:19], v[238:241], v[210:213], v[16:19]
	v_mfma_f32_16x16x32_bf16 v[12:15], v[230:233], v[218:221], v[12:15]
	v_mfma_f32_16x16x32_bf16 v[8:11], v[238:241], v[218:221], v[8:11]
	v_mfma_f32_16x16x32_bf16 v[4:7], v[230:233], v[226:229], v[4:7]
	v_mfma_f32_16x16x32_bf16 v[0:3], v[238:241], v[226:229], v[0:3]
	s_add_u32 s34, s34, 0x100
	s_addc_u32 s35, s35, 0
	s_add_u32 s70, s70, 0x100
	s_addc_u32 s71, s71, 0
	s_cmp_ge_i32 s49, s36
	s_cbranch_scc1 .Lrot_exit_1
	s_cmp_eq_u32 s39, s49
	s_cselect_b64 s[54:55], -1, 0
	s_and_b64 vcc, exec, s[54:55]
	v_mov_b64_e32 v[152:153], v[144:145]
	v_mov_b64_e32 v[154:155], v[142:143]
	s_mov_b64 s[88:89], s[68:69]
	s_mov_b64 s[82:83], s[66:67]
	v_mov_b32_e32 v156, v148
	v_mov_b32_e32 v136, v146
	s_mov_b64 s[92:93], s[42:43]
	s_cbranch_vccnz .Lrot_join_1
	v_mov_b64_e32 v[152:153], v[128:129]
	v_mov_b64_e32 v[154:155], v[132:133]
	s_mov_b64 s[88:89], s[12:13]
	s_mov_b64 s[82:83], s[14:15]
	v_mov_b32_e32 v156, v130
	v_mov_b32_e32 v136, v131
	s_mov_b64 s[92:93], s[70:71]

; #define PG8_STAGE(bufoff, gbase, v0, v1) do { \
;         __builtin_amdgcn_global_load_lds((const unsigned*)((const char*)(gbase) + (v0)), (LAS unsigned*)(lds + (bufoff) + ldsw), 16, 0, 0); \
;         __builtin_amdgcn_global_load_lds((const unsigned*)((const char*)(gbase) + (v1)), (LAS unsigned*)(lds + (bufoff) + ldsw + 8192), 16, 0, 0); } while (0)
; #define PG8_LDA(dst, b, h) do { _Pragma("unroll") for (int m = 0; m < 4; ++m) _Pragma("unroll") for (int k = 0; k < 2; ++k) dst[m][k] = *(const LAS bf16x8*)(lds + PG8_SA(b, h) + aoff + m * 2048 + k * 1024); } while (0)
; #define PG8_LDB(dst, b, h) do { _Pragma("unroll") for (int n = 0; n < 2; ++n) _Pragma("unroll") for (int k = 0; k < 2; ++k) dst[n][k] = *(const LAS bf16x8*)(lds + PG8_SB(b, h) + boff + n * 2048 + k * 1024); } while (0)
; #define PG8_MMA(ai, bj, At, Bt) do { __builtin_amdgcn_s_setprio(1); _Pragma("unroll") for (int m = 0; m < 4; ++m) _Pragma("unroll") for (int n = 0; n < 2; ++n) _Pragma("unroll") for (int k = 0; k < 2; ++k) \
;         acc[ai][bj][m][n] = __builtin_amdgcn_mfma_f32_16x16x32_bf16(Bt[n][k], At[m][k], acc[ai][bj][m][n], 0, 0, 0); __builtin_amdgcn_s_setprio(0); } while (0)
; #define PG8_WAIT_V(n) asm volatile("s_waitcnt vmcnt(" #n ")" ::: "memory")
; #define PG8_WAIT_L(n) asm volatile("s_waitcnt lgkmcnt(" #n ")" ::: "memory")
; #define PG8_BAR __builtin_amdgcn_s_barrier()
; #define PG8_SCHED __builtin_amdgcn_sched_barrier(0)
; template <class Epi, class Sched>
; __device__ __forceinline__ void gemm_phase(LAS unsigned char* lds, const Sched& S, const Epi& E) {
;     ...
;             PG8_LDB(B0, 0, 0); PG8_SCHED; PG8_LDA(At, 0, 0); PG8_STAGE(PG8_SA(1, 1), a1 + hA, vA0, vA1);
;             PG8_WAIT_L(8); PG8_BAR; PG8_WAIT_L(0); PG8_MMA(0, 0, At, B0); PG8_BAR; PG8_SCHED;
;             PG8_LDB(B1, 0, 1); PG8_STAGE(PG8_SB(0, 0), b2, xB0, xB1);
;             PG8_BAR; PG8_WAIT_L(0); PG8_MMA(0, 1, At, B1); PG8_BAR;
;             PG8_LDA(At, 0, 1); PG8_STAGE(PG8_SA(0, 0), a2, xA0, xA1);
;             PG8_BAR; PG8_WAIT_L(0); PG8_MMA(1, 0, At, B0); PG8_BAR; PG8_SCHED;
;             PG8_STAGE(PG8_SB(0, 1), b2 + xhB, xB0, xB1);
;             PG8_WAIT_V(6); PG8_BAR; PG8_MMA(1, 1, At, B1); PG8_BAR;
.Lrot_body_2:
	ds_read_b128 v[150:153], v138
	ds_read_b128 v[154:157], v138 offset:1024
	ds_read_b128 v[158:161], v138 offset:2048
	ds_read_b128 v[182:185], v138 offset:3072
	v_lshl_add_u64 v[138:139], s[34:35], 0, v[136:137]
	s_add_i32 m0, s50, 0xc000
	ds_read_b128 v[186:189], v148
	ds_read_b128 v[190:193], v148 offset:1024
	ds_read_b128 v[194:197], v148 offset:2048
	ds_read_b128 v[198:201], v148 offset:3072
	ds_read_b128 v[202:205], v148 offset:4096
	ds_read_b128 v[206:209], v148 offset:5120
	ds_read_b128 v[210:213], v148 offset:6144
	ds_read_b128 v[214:217], v148 offset:7168
	global_load_lds_dwordx4 v[138:139], off
	v_lshl_add_u64 v[138:139], s[34:35], 0, v[132:133]
	s_add_i32 m0, s50, 0xe000
	s_nop 0
	global_load_lds_dwordx4 v[138:139], off
	s_waitcnt lgkmcnt(8)
	s_barrier
	s_waitcnt lgkmcnt(0)
	v_mfma_f32_16x16x32_bf16 v[124:127], v[150:153], v[186:189], v[124:127]
	v_mfma_f32_16x16x32_bf16 v[120:123], v[158:161], v[186:189], v[120:123]
	v_mfma_f32_16x16x32_bf16 v[108:111], v[150:153], v[194:197], v[108:111]
	v_mfma_f32_16x16x32_bf16 v[104:107], v[158:161], v[194:197], v[104:107]
	v_mfma_f32_16x16x32_bf16 v[92:95], v[150:153], v[202:205], v[92:95]
	v_mfma_f32_16x16x32_bf16 v[88:91], v[158:161], v[202:205], v[88:91]
	v_mfma_f32_16x16x32_bf16 v[76:79], v[150:153], v[210:213], v[76:79]
	v_mfma_f32_16x16x32_bf16 v[72:75], v[158:161], v[210:213], v[72:75]
	v_mfma_f32_16x16x32_bf16 v[124:127], v[154:157], v[190:193], v[124:127]
	v_mfma_f32_16x16x32_bf16 v[120:123], v[182:185], v[190:193], v[120:123]
	v_mfma_f32_16x16x32_bf16 v[108:111], v[154:157], v[198:201], v[108:111]
	v_mfma_f32_16x16x32_bf16 v[104:107], v[182:185], v[198:201], v[104:107]
	v_mfma_f32_16x16x32_bf16 v[92:95], v[154:157], v[206:209], v[92:95]
	v_mfma_f32_16x16x32_bf16 v[88:91], v[182:185], v[206:209], v[88:91]
	v_mfma_f32_16x16x32_bf16 v[76:79], v[154:157], v[214:217], v[76:79]
	v_mfma_f32_16x16x32_bf16 v[72:75], v[182:185], v[214:217], v[72:75]
	s_barrier
	s_add_i32 s71, 0, 0x14000
	v_add_u32_e32 v138, s71, v147
	s_add_i32 s23, s23, s49
	ds_read_b128 v[218:221], v138
	ds_read_b128 v[222:225], v138 offset:1024
	ds_read_b128 v[226:229], v138 offset:2048
	ds_read_b128 v[230:233], v138 offset:3072
	v_lshl_add_u64 v[138:139], s[40:41], 0, v[142:143]
	s_mov_b32 m0, s23
	v_lshl_add_u64 v[140:141], s[40:41], 0, v[134:135]
	global_load_lds_dwordx4 v[138:139], off
	s_add_i32 m0, s23, 0x2000
	s_nop 0
	global_load_lds_dwordx4 v[140:141], off
	s_mov_b32 m0, s50
	v_lshl_add_u64 v[234:235], s[42:43], 0, v[142:143]
	s_barrier
	s_waitcnt lgkmcnt(0)
	v_mfma_f32_16x16x32_bf16 v[116:119], v[218:221], v[186:189], v[116:119]
	v_mfma_f32_16x16x32_bf16 v[112:115], v[226:229], v[186:189], v[112:115]
	v_mfma_f32_16x16x32_bf16 v[100:103], v[218:221], v[194:197], v[100:103]
	v_mfma_f32_16x16x32_bf16 v[96:99], v[226:229], v[194:197], v[96:99]
	v_mfma_f32_16x16x32_bf16 v[84:87], v[218:221], v[202:205], v[84:87]
	v_mfma_f32_16x16x32_bf16 v[80:83], v[226:229], v[202:205], v[80:83]
	v_mfma_f32_16x16x32_bf16 v[68:71], v[218:221], v[210:213], v[68:71]
	v_mfma_f32_16x16x32_bf16 v[64:67], v[226:229], v[210:213], v[64:67]
	v_mfma_f32_16x16x32_bf16 v[116:119], v[222:225], v[190:193], v[116:119]
	v_mfma_f32_16x16x32_bf16 v[112:115], v[230:233], v[190:193], v[112:115]
	v_mfma_f32_16x16x32_bf16 v[100:103], v[222:225], v[198:201], v[100:103]
	v_mfma_f32_16x16x32_bf16 v[96:99], v[230:233], v[198:201], v[96:99]
	v_mfma_f32_16x16x32_bf16 v[84:87], v[222:225], v[206:209], v[84:87]
	v_mfma_f32_16x16x32_bf16 v[80:83], v[230:233], v[206:209], v[80:83]
	v_mfma_f32_16x16x32_bf16 v[68:71], v[222:225], v[214:217], v[68:71]
	v_mfma_f32_16x16x32_bf16 v[64:67], v[230:233], v[214:217], v[64:67]
	s_barrier
	ds_read_b128 v[186:189], v148 offset:16384
	ds_read_b128 v[190:193], v148 offset:17408
	ds_read_b128 v[194:197], v148 offset:18432
	ds_read_b128 v[198:201], v148 offset:19456
	ds_read_b128 v[202:205], v148 offset:20480
	ds_read_b128 v[206:209], v148 offset:21504
	ds_read_b128 v[210:213], v148 offset:22528
	ds_read_b128 v[214:217], v148 offset:23552
	global_load_lds_dwordx4 v[234:235], off
	v_lshl_add_u64 v[236:237], s[42:43], 0, v[134:135]
	s_mov_b32 m0, s51
	s_nop 0
	global_load_lds_dwordx4 v[236:237], off
	s_barrier
	s_waitcnt lgkmcnt(0)
	v_mfma_f32_16x16x32_bf16 v[60:63], v[150:153], v[186:189], v[60:63]
	v_mfma_f32_16x16x32_bf16 v[56:59], v[158:161], v[186:189], v[56:59]
	v_mfma_f32_16x16x32_bf16 v[44:47], v[150:153], v[194:197], v[44:47]
	v_mfma_f32_16x16x32_bf16 v[40:43], v[158:161], v[194:197], v[40:43]
	v_mfma_f32_16x16x32_bf16 v[28:31], v[150:153], v[202:205], v[28:31]
	v_mfma_f32_16x16x32_bf16 v[24:27], v[158:161], v[202:205], v[24:27]
	v_mfma_f32_16x16x32_bf16 v[12:15], v[150:153], v[210:213], v[12:15]
	v_mfma_f32_16x16x32_bf16 v[8:11], v[158:161], v[210:213], v[8:11]
	v_mfma_f32_16x16x32_bf16 v[60:63], v[154:157], v[190:193], v[60:63]
	v_mfma_f32_16x16x32_bf16 v[56:59], v[182:185], v[190:193], v[56:59]
	v_mfma_f32_16x16x32_bf16 v[44:47], v[154:157], v[198:201], v[44:47]
	v_mfma_f32_16x16x32_bf16 v[40:43], v[182:185], v[198:201], v[40:43]
	v_mfma_f32_16x16x32_bf16 v[28:31], v[154:157], v[206:209], v[28:31]
	v_mfma_f32_16x16x32_bf16 v[24:27], v[182:185], v[206:209], v[24:27]
	v_mfma_f32_16x16x32_bf16 v[12:15], v[154:157], v[214:217], v[12:15]
	v_mfma_f32_16x16x32_bf16 v[8:11], v[182:185], v[214:217], v[8:11]
	s_barrier
	s_add_u32 s82, s40, 0x80000
	s_addc_u32 s83, s41, 0
	s_add_i32 s23, s71, s49
	v_lshl_add_u64 v[150:151], s[82:83], 0, v[142:143]
	s_mov_b32 m0, s23
	s_nop 0
	global_load_lds_dwordx4 v[150:151], off
	v_lshl_add_u64 v[150:151], s[82:83], 0, v[134:135]
	s_add_i32 m0, s23, 0x2000
	s_nop 0
	global_load_lds_dwordx4 v[150:151], off
	s_add_i32 s23, 0, 0x18000
	v_add_u32_e32 v149, s23, v147
	s_waitcnt vmcnt(6)
	s_barrier
; #define PG8_STAGE(bufoff, gbase, v0, v1) do { \
;         __builtin_amdgcn_global_load_lds((const unsigned*)((const char*)(gbase) + (v0)), (LAS unsigned*)(lds + (bufoff) + ldsw), 16, 0, 0); \
;         __builtin_amdgcn_global_load_lds((const unsigned*)((const char*)(gbase) + (v1)), (LAS unsigned*)(lds + (bufoff) + ldsw + 8192), 16, 0, 0); } while (0)
; #define PG8_LDA(dst, b, h) do { _Pragma("unroll") for (int m = 0; m < 4; ++m) _Pragma("unroll") for (int k = 0; k < 2; ++k) dst[m][k] = *(const LAS bf16x8*)(lds + PG8_SA(b, h) + aoff + m * 2048 + k * 1024); } while (0)
; #define PG8_LDB(dst, b, h) do { _Pragma("unroll") for (int n = 0; n < 2; ++n) _Pragma("unroll") for (int k = 0; k < 2; ++k) dst[n][k] = *(const LAS bf16x8*)(lds + PG8_SB(b, h) + boff + n * 2048 + k * 1024); } while (0)
; #define PG8_MMA(ai, bj, At, Bt) do { __builtin_amdgcn_s_setprio(1); _Pragma("unroll") for (int m = 0; m < 4; ++m) _Pragma("unroll") for (int n = 0; n < 2; ++n) _Pragma("unroll") for (int k = 0; k < 2; ++k) \
;         acc[ai][bj][m][n] = __builtin_amdgcn_mfma_f32_16x16x32_bf16(Bt[n][k], At[m][k], acc[ai][bj][m][n], 0, 0, 0); __builtin_amdgcn_s_setprio(0); } while (0)
; #define PG8_WAIT_V(n) asm volatile("s_waitcnt vmcnt(" #n ")" ::: "memory")
; #define PG8_WAIT_L(n) asm volatile("s_waitcnt lgkmcnt(" #n ")" ::: "memory")
; #define PG8_BAR __builtin_amdgcn_s_barrier()
; #define PG8_SCHED __builtin_amdgcn_sched_barrier(0)
; template <class Epi, class Sched>
; __device__ __forceinline__ void gemm_phase(LAS unsigned char* lds, const Sched& S, const Epi& E) {
;     ...
;             PG8_WAIT_V(6); PG8_BAR; PG8_MMA(1, 1, At, B1); PG8_BAR;
;             PG8_LDB(B0, 1, 0); PG8_SCHED; PG8_LDA(At, 1, 0); PG8_STAGE(PG8_SA(0, 1), a2 + xhA, xA0, xA1);
;             PG8_WAIT_L(8); PG8_BAR; PG8_WAIT_L(0); PG8_MMA(0, 0, At, B0); PG8_BAR; PG8_SCHED;
;             PG8_LDB(B1, 1, 1); PG8_STAGE(PG8_SB(1, 0), b3, xB0, xB1);
;             PG8_BAR; PG8_WAIT_L(0); PG8_MMA(0, 1, At, B1); PG8_BAR;
;             PG8_LDA(At, 1, 1); PG8_STAGE(PG8_SA(1, 0), a3, xA0, xA1);
;             PG8_BAR; PG8_WAIT_L(0); PG8_MMA(1, 0, At, B0); PG8_BAR; PG8_SCHED;
	v_mfma_f32_16x16x32_bf16 v[52:55], v[218:221], v[186:189], v[52:55]
	v_mfma_f32_16x16x32_bf16 v[48:51], v[226:229], v[186:189], v[48:51]
	v_mfma_f32_16x16x32_bf16 v[36:39], v[218:221], v[194:197], v[36:39]
	v_mfma_f32_16x16x32_bf16 v[32:35], v[226:229], v[194:197], v[32:35]
	v_mfma_f32_16x16x32_bf16 v[20:23], v[218:221], v[202:205], v[20:23]
	v_mfma_f32_16x16x32_bf16 v[16:19], v[226:229], v[202:205], v[16:19]
	v_mfma_f32_16x16x32_bf16 v[4:7], v[218:221], v[210:213], v[4:7]
	v_mfma_f32_16x16x32_bf16 v[0:3], v[226:229], v[210:213], v[0:3]
	v_mfma_f32_16x16x32_bf16 v[52:55], v[222:225], v[190:193], v[52:55]
	v_mfma_f32_16x16x32_bf16 v[48:51], v[230:233], v[190:193], v[48:51]
	v_mfma_f32_16x16x32_bf16 v[36:39], v[222:225], v[198:201], v[36:39]
	v_mfma_f32_16x16x32_bf16 v[32:35], v[230:233], v[198:201], v[32:35]
	v_mfma_f32_16x16x32_bf16 v[20:23], v[222:225], v[206:209], v[20:23]
	v_mfma_f32_16x16x32_bf16 v[16:19], v[230:233], v[206:209], v[16:19]
	v_mfma_f32_16x16x32_bf16 v[4:7], v[222:225], v[214:217], v[4:7]
	v_mfma_f32_16x16x32_bf16 v[0:3], v[230:233], v[214:217], v[0:3]
	s_barrier
	ds_read_b128 v[150:153], v149
	ds_read_b128 v[154:157], v149 offset:1024
	ds_read_b128 v[158:161], v149 offset:2048
	ds_read_b128 v[182:185], v149 offset:3072
	s_add_u32 s42, s42, 0x80000
	s_addc_u32 s43, s43, 0
	s_mov_b32 m0, s54
	v_lshl_add_u64 v[218:219], s[42:43], 0, v[142:143]
	ds_read_b128 v[186:189], v148 offset:32768
	ds_read_b128 v[190:193], v148 offset:33792
	ds_read_b128 v[194:197], v148 offset:34816
	ds_read_b128 v[198:201], v148 offset:35840
	ds_read_b128 v[202:205], v148 offset:36864
	ds_read_b128 v[206:209], v148 offset:37888
	ds_read_b128 v[210:213], v148 offset:38912
	ds_read_b128 v[214:217], v148 offset:39936
	global_load_lds_dwordx4 v[218:219], off
	v_lshl_add_u64 v[218:219], s[42:43], 0, v[134:135]
	s_mov_b32 m0, s55
	s_nop 0
	global_load_lds_dwordx4 v[218:219], off
	s_waitcnt lgkmcnt(8)
	s_barrier
	s_waitcnt lgkmcnt(0)
	v_mfma_f32_16x16x32_bf16 v[124:127], v[150:153], v[186:189], v[124:127]
	v_mfma_f32_16x16x32_bf16 v[120:123], v[158:161], v[186:189], v[120:123]
	v_mfma_f32_16x16x32_bf16 v[108:111], v[150:153], v[194:197], v[108:111]
	v_mfma_f32_16x16x32_bf16 v[104:107], v[158:161], v[194:197], v[104:107]
	v_mfma_f32_16x16x32_bf16 v[92:95], v[150:153], v[202:205], v[92:95]
	v_mfma_f32_16x16x32_bf16 v[88:91], v[158:161], v[202:205], v[88:91]
	v_mfma_f32_16x16x32_bf16 v[76:79], v[150:153], v[210:213], v[76:79]
	v_mfma_f32_16x16x32_bf16 v[72:75], v[158:161], v[210:213], v[72:75]
	v_mfma_f32_16x16x32_bf16 v[124:127], v[154:157], v[190:193], v[124:127]
	v_mfma_f32_16x16x32_bf16 v[120:123], v[182:185], v[190:193], v[120:123]
	v_mfma_f32_16x16x32_bf16 v[108:111], v[154:157], v[198:201], v[108:111]
	v_mfma_f32_16x16x32_bf16 v[104:107], v[182:185], v[198:201], v[104:107]
	v_mfma_f32_16x16x32_bf16 v[92:95], v[154:157], v[206:209], v[92:95]
	v_mfma_f32_16x16x32_bf16 v[88:91], v[182:185], v[206:209], v[88:91]
	v_mfma_f32_16x16x32_bf16 v[76:79], v[154:157], v[214:217], v[76:79]
	v_mfma_f32_16x16x32_bf16 v[72:75], v[182:185], v[214:217], v[72:75]
	s_barrier
	s_add_i32 s42, 0, 0x1c000
	s_add_i32 s23, s23, s49
	v_add_u32_e32 v149, s42, v147
	v_lshl_add_u64 v[138:139], v[138:139], 0, s[44:45]
	s_mov_b32 m0, s23
	ds_read_b128 v[218:221], v149
	ds_read_b128 v[222:225], v149 offset:1024
	ds_read_b128 v[226:229], v149 offset:2048
	ds_read_b128 v[230:233], v149 offset:3072
	global_load_lds_dwordx4 v[138:139], off
	v_lshl_add_u64 v[138:139], v[140:141], 0, s[44:45]
	s_add_i32 m0, s23, 0x2000
	s_nop 0
	global_load_lds_dwordx4 v[138:139], off
	s_mov_b32 m0, s66
	v_lshl_add_u64 v[138:139], v[234:235], 0, s[44:45]
	s_barrier
; #define PG8_STAGE(bufoff, gbase, v0, v1) do { \
;         __builtin_amdgcn_global_load_lds((const unsigned*)((const char*)(gbase) + (v0)), (LAS unsigned*)(lds + (bufoff) + ldsw), 16, 0, 0); \
;         __builtin_amdgcn_global_load_lds((const unsigned*)((const char*)(gbase) + (v1)), (LAS unsigned*)(lds + (bufoff) + ldsw + 8192), 16, 0, 0); } while (0)
; #define PG8_LDA(dst, b, h) do { _Pragma("unroll") for (int m = 0; m < 4; ++m) _Pragma("unroll") for (int k = 0; k < 2; ++k) dst[m][k] = *(const LAS bf16x8*)(lds + PG8_SA(b, h) + aoff + m * 2048 + k * 1024); } while (0)
; #define PG8_MMA(ai, bj, At, Bt) do { __builtin_amdgcn_s_setprio(1); _Pragma("unroll") for (int m = 0; m < 4; ++m) _Pragma("unroll") for (int n = 0; n < 2; ++n) _Pragma("unroll") for (int k = 0; k < 2; ++k) \
;         acc[ai][bj][m][n] = __builtin_amdgcn_mfma_f32_16x16x32_bf16(Bt[n][k], At[m][k], acc[ai][bj][m][n], 0, 0, 0); __builtin_amdgcn_s_setprio(0); } while (0)
; #define PG8_WAIT_V(n) asm volatile("s_waitcnt vmcnt(" #n ")" ::: "memory")
; #define PG8_WAIT_L(n) asm volatile("s_waitcnt lgkmcnt(" #n ")" ::: "memory")
; #define PG8_BAR __builtin_amdgcn_s_barrier()
; #define PG8_SCHED __builtin_amdgcn_sched_barrier(0)
; template <class Epi, class Sched>
; __device__ __forceinline__ void gemm_phase(LAS unsigned char* lds, const Sched& S, const Epi& E) {
;     ...
;         for (int t = 0; t < nt; t += 2) {
;             const bool last = (t == nt - 2);
;             const char* a1 = cA + (size_t)(t + 1) * kstep;
;             const char* a2 = last ? nA : cA + (size_t)(t + 2) * kstep; const char* b2 = last ? nB : cB + (size_t)(t + 2) * kstep;
;             const char* a3 = a2 + kstep; const char* b3 = b2 + kstep;
;             const unsigned xA0 = last ? nvA0 : vA0, xA1 = last ? nvA1 : vA1, xB0 = last ? nvB0 : vB0, xB1 = last ? nvB1 : vB1;
;     ...
;             PG8_BAR; PG8_WAIT_L(0); PG8_MMA(0, 1, At, B1); PG8_BAR;
;             PG8_LDA(At, 1, 1); PG8_STAGE(PG8_SA(1, 0), a3, xA0, xA1);
;             PG8_BAR; PG8_WAIT_L(0); PG8_MMA(1, 0, At, B0); PG8_BAR; PG8_SCHED;
;             PG8_STAGE(PG8_SB(1, 1), b3 + xhB, xB0, xB1);
;             PG8_WAIT_V(6); PG8_BAR; PG8_MMA(1, 1, At, B1); PG8_BAR;
	s_waitcnt lgkmcnt(0)
	v_mfma_f32_16x16x32_bf16 v[116:119], v[218:221], v[186:189], v[116:119]
	v_mfma_f32_16x16x32_bf16 v[112:115], v[226:229], v[186:189], v[112:115]
	v_mfma_f32_16x16x32_bf16 v[100:103], v[218:221], v[194:197], v[100:103]
	v_mfma_f32_16x16x32_bf16 v[96:99], v[226:229], v[194:197], v[96:99]
	v_mfma_f32_16x16x32_bf16 v[84:87], v[218:221], v[202:205], v[84:87]
	v_mfma_f32_16x16x32_bf16 v[80:83], v[226:229], v[202:205], v[80:83]
	v_mfma_f32_16x16x32_bf16 v[68:71], v[218:221], v[210:213], v[68:71]
	v_mfma_f32_16x16x32_bf16 v[64:67], v[226:229], v[210:213], v[64:67]
	v_mfma_f32_16x16x32_bf16 v[116:119], v[222:225], v[190:193], v[116:119]
	v_mfma_f32_16x16x32_bf16 v[112:115], v[230:233], v[190:193], v[112:115]
	v_mfma_f32_16x16x32_bf16 v[100:103], v[222:225], v[198:201], v[100:103]
	v_mfma_f32_16x16x32_bf16 v[96:99], v[230:233], v[198:201], v[96:99]
	v_mfma_f32_16x16x32_bf16 v[84:87], v[222:225], v[206:209], v[84:87]
	v_mfma_f32_16x16x32_bf16 v[80:83], v[230:233], v[206:209], v[80:83]
	v_mfma_f32_16x16x32_bf16 v[68:71], v[222:225], v[214:217], v[68:71]
	v_mfma_f32_16x16x32_bf16 v[64:67], v[230:233], v[214:217], v[64:67]
	s_barrier
	ds_read_b128 v[186:189], v148 offset:49152
	ds_read_b128 v[190:193], v148 offset:50176
	ds_read_b128 v[194:197], v148 offset:51200
	ds_read_b128 v[198:201], v148 offset:52224
	ds_read_b128 v[202:205], v148 offset:53248
	ds_read_b128 v[206:209], v148 offset:54272
	ds_read_b128 v[210:213], v148 offset:55296
	ds_read_b128 v[214:217], v148 offset:56320
	global_load_lds_dwordx4 v[138:139], off
	v_lshl_add_u64 v[138:139], v[236:237], 0, s[44:45]
	s_mov_b32 m0, s67
	s_nop 0
	global_load_lds_dwordx4 v[138:139], off
	s_barrier
	s_waitcnt lgkmcnt(0)
	v_mfma_f32_16x16x32_bf16 v[60:63], v[150:153], v[186:189], v[60:63]
	v_mfma_f32_16x16x32_bf16 v[56:59], v[158:161], v[186:189], v[56:59]
	v_mfma_f32_16x16x32_bf16 v[44:47], v[150:153], v[194:197], v[44:47]
	v_mfma_f32_16x16x32_bf16 v[40:43], v[158:161], v[194:197], v[40:43]
	v_mfma_f32_16x16x32_bf16 v[28:31], v[150:153], v[202:205], v[28:31]
	v_mfma_f32_16x16x32_bf16 v[24:27], v[158:161], v[202:205], v[24:27]
	v_mfma_f32_16x16x32_bf16 v[12:15], v[150:153], v[210:213], v[12:15]
	v_mfma_f32_16x16x32_bf16 v[8:11], v[158:161], v[210:213], v[8:11]
	v_mfma_f32_16x16x32_bf16 v[60:63], v[154:157], v[190:193], v[60:63]
	v_mfma_f32_16x16x32_bf16 v[56:59], v[182:185], v[190:193], v[56:59]
	v_mfma_f32_16x16x32_bf16 v[44:47], v[154:157], v[198:201], v[44:47]
	v_mfma_f32_16x16x32_bf16 v[40:43], v[182:185], v[198:201], v[40:43]
	v_mfma_f32_16x16x32_bf16 v[28:31], v[154:157], v[206:209], v[28:31]
	v_mfma_f32_16x16x32_bf16 v[24:27], v[182:185], v[206:209], v[24:27]
	v_mfma_f32_16x16x32_bf16 v[12:15], v[154:157], v[214:217], v[12:15]
	v_mfma_f32_16x16x32_bf16 v[8:11], v[182:185], v[214:217], v[8:11]
	s_barrier
	s_add_u32 s40, s40, 0x80080
	s_addc_u32 s41, s41, 0
	s_add_i32 s23, s42, s49
	v_lshl_add_u64 v[138:139], s[40:41], 0, v[142:143]
	s_mov_b32 m0, s23
	v_lshl_add_u64 v[134:135], s[40:41], 0, v[134:135]
	global_load_lds_dwordx4 v[138:139], off
	s_add_i32 m0, s23, 0x2000
	s_nop 0
	global_load_lds_dwordx4 v[134:135], off
	s_waitcnt vmcnt(6)
	s_barrier
	v_mfma_f32_16x16x32_bf16 v[52:55], v[218:221], v[186:189], v[52:55]
	v_mfma_f32_16x16x32_bf16 v[48:51], v[226:229], v[186:189], v[48:51]
	v_mfma_f32_16x16x32_bf16 v[36:39], v[218:221], v[194:197], v[36:39]
	v_mfma_f32_16x16x32_bf16 v[32:35], v[226:229], v[194:197], v[32:35]
	v_mfma_f32_16x16x32_bf16 v[20:23], v[218:221], v[202:205], v[20:23]
	v_mfma_f32_16x16x32_bf16 v[16:19], v[226:229], v[202:205], v[16:19]
	v_mfma_f32_16x16x32_bf16 v[4:7], v[218:221], v[210:213], v[4:7]
	v_mfma_f32_16x16x32_bf16 v[0:3], v[226:229], v[210:213], v[0:3]
	v_mfma_f32_16x16x32_bf16 v[52:55], v[222:225], v[190:193], v[52:55]
	v_mfma_f32_16x16x32_bf16 v[48:51], v[230:233], v[190:193], v[48:51]
	v_mfma_f32_16x16x32_bf16 v[36:39], v[222:225], v[198:201], v[36:39]
	v_mfma_f32_16x16x32_bf16 v[32:35], v[230:233], v[198:201], v[32:35]
	v_mfma_f32_16x16x32_bf16 v[20:23], v[222:225], v[206:209], v[20:23]
	v_mfma_f32_16x16x32_bf16 v[16:19], v[230:233], v[206:209], v[16:19]
	v_mfma_f32_16x16x32_bf16 v[4:7], v[222:225], v[214:217], v[4:7]
	v_mfma_f32_16x16x32_bf16 v[0:3], v[230:233], v[214:217], v[0:3]
	s_add_i32 s21, s21, 2
	s_add_u32 s34, s34, 0x100
	s_addc_u32 s35, s35, 0
	s_add_u32 s38, s38, 0x100
	s_addc_u32 s39, s39, 0
	s_cmp_gt_u32 s21, 29
	s_cbranch_scc1 .Lrot_exit_2
	s_cmp_eq_u32 s21, 28
	s_cselect_b64 s[42:43], -1, 0
	s_and_b64 vcc, exec, s[42:43]
	v_mov_b64_e32 v[134:135], v[130:131]
	v_mov_b64_e32 v[142:143], v[128:129]
	s_mov_b64 s[40:41], s[26:27]
	s_cbranch_vccnz .Lrot_join_2
	v_mov_b64_e32 v[134:135], v[132:133]
	v_mov_b64_e32 v[142:143], v[136:137]
	s_mov_b64 s[40:41], s[38:39]

; #define PG8_STAGE(bufoff, gbase, v0, v1) do { \
;         __builtin_amdgcn_global_load_lds((const unsigned*)((const char*)(gbase) + (v0)), (LAS unsigned*)(lds + (bufoff) + ldsw), 16, 0, 0); \
;         __builtin_amdgcn_global_load_lds((const unsigned*)((const char*)(gbase) + (v1)), (LAS unsigned*)(lds + (bufoff) + ldsw + 8192), 16, 0, 0); } while (0)
; #define PG8_LDA(dst, b, h) do { _Pragma("unroll") for (int m = 0; m < 4; ++m) _Pragma("unroll") for (int k = 0; k < 2; ++k) dst[m][k] = *(const LAS bf16x8*)(lds + PG8_SA(b, h) + aoff + m * 2048 + k * 1024); } while (0)
; #define PG8_LDB(dst, b, h) do { _Pragma("unroll") for (int n = 0; n < 2; ++n) _Pragma("unroll") for (int k = 0; k < 2; ++k) dst[n][k] = *(const LAS bf16x8*)(lds + PG8_SB(b, h) + boff + n * 2048 + k * 1024); } while (0)
; #define PG8_MMA(ai, bj, At, Bt) do { __builtin_amdgcn_s_setprio(1); _Pragma("unroll") for (int m = 0; m < 4; ++m) _Pragma("unroll") for (int n = 0; n < 2; ++n) _Pragma("unroll") for (int k = 0; k < 2; ++k) \
;         acc[ai][bj][m][n] = __builtin_amdgcn_mfma_f32_16x16x32_bf16(Bt[n][k], At[m][k], acc[ai][bj][m][n], 0, 0, 0); __builtin_amdgcn_s_setprio(0); } while (0)
; #define PG8_WAIT_V(n) asm volatile("s_waitcnt vmcnt(" #n ")" ::: "memory")
; #define PG8_WAIT_L(n) asm volatile("s_waitcnt lgkmcnt(" #n ")" ::: "memory")
; #define PG8_BAR __builtin_amdgcn_s_barrier()
; #define PG8_SCHED __builtin_amdgcn_sched_barrier(0)
; template <class Epi, class Sched>
; __device__ __forceinline__ void gemm_phase(LAS unsigned char* lds, const Sched& S, const Epi& E) {
;     ...
;             PG8_LDB(B0, 0, 0); PG8_SCHED; PG8_LDA(At, 0, 0); PG8_STAGE(PG8_SA(1, 1), a1 + hA, vA0, vA1);
;             PG8_WAIT_L(8); PG8_BAR; PG8_WAIT_L(0); PG8_MMA(0, 0, At, B0); PG8_BAR; PG8_SCHED;
;             PG8_LDB(B1, 0, 1); PG8_STAGE(PG8_SB(0, 0), b2, xB0, xB1);
;             PG8_BAR; PG8_WAIT_L(0); PG8_MMA(0, 1, At, B1); PG8_BAR;
;             PG8_LDA(At, 0, 1); PG8_STAGE(PG8_SA(0, 0), a2, xA0, xA1);
;             PG8_BAR; PG8_WAIT_L(0); PG8_MMA(1, 0, At, B0); PG8_BAR; PG8_SCHED;
;             PG8_STAGE(PG8_SB(0, 1), b2 + xhB, xB0, xB1);
;             PG8_WAIT_V(6); PG8_BAR; PG8_MMA(1, 1, At, B1); PG8_BAR;
;             PG8_LDB(B0, 1, 0); PG8_SCHED; PG8_LDA(At, 1, 0); PG8_STAGE(PG8_SA(0, 1), a2 + xhA, xA0, xA1);
.Lrot_body_3:
	ds_read_b128 v[158:161], v138
	ds_read_b128 v[182:185], v138 offset:1024
	ds_read_b128 v[186:189], v138 offset:2048
	ds_read_b128 v[190:193], v138 offset:3072
	v_lshl_add_u64 v[138:139], s[26:27], 0, v[132:133]
	s_add_i32 m0, s48, 0xc000
	ds_read_b128 v[194:197], v143
	ds_read_b128 v[198:201], v143 offset:1024
	ds_read_b128 v[202:205], v143 offset:2048
	ds_read_b128 v[206:209], v143 offset:3072
	ds_read_b128 v[210:213], v143 offset:4096
	ds_read_b128 v[214:217], v143 offset:5120
	ds_read_b128 v[218:221], v143 offset:6144
	ds_read_b128 v[222:225], v143 offset:7168
	global_load_lds_dwordx4 v[138:139], off
	v_lshl_add_u64 v[138:139], s[26:27], 0, v[134:135]
	s_add_i32 m0, s48, 0xe000
	s_nop 0
	global_load_lds_dwordx4 v[138:139], off
	s_waitcnt lgkmcnt(8)
	s_barrier
	s_waitcnt lgkmcnt(0)
	v_mfma_f32_16x16x32_bf16 v[124:127], v[158:161], v[194:197], v[124:127]
	v_mfma_f32_16x16x32_bf16 v[120:123], v[186:189], v[194:197], v[120:123]
	v_mfma_f32_16x16x32_bf16 v[112:115], v[158:161], v[202:205], v[112:115]
	v_mfma_f32_16x16x32_bf16 v[104:107], v[186:189], v[202:205], v[104:107]
	v_mfma_f32_16x16x32_bf16 v[96:99], v[158:161], v[210:213], v[96:99]
	v_mfma_f32_16x16x32_bf16 v[88:91], v[186:189], v[210:213], v[88:91]
	v_mfma_f32_16x16x32_bf16 v[80:83], v[158:161], v[218:221], v[80:83]
	v_mfma_f32_16x16x32_bf16 v[72:75], v[186:189], v[218:221], v[72:75]
	v_mfma_f32_16x16x32_bf16 v[124:127], v[182:185], v[198:201], v[124:127]
	v_mfma_f32_16x16x32_bf16 v[120:123], v[190:193], v[198:201], v[120:123]
	v_mfma_f32_16x16x32_bf16 v[112:115], v[182:185], v[206:209], v[112:115]
	v_mfma_f32_16x16x32_bf16 v[104:107], v[190:193], v[206:209], v[104:107]
	v_mfma_f32_16x16x32_bf16 v[96:99], v[182:185], v[214:217], v[96:99]
	v_mfma_f32_16x16x32_bf16 v[88:91], v[190:193], v[214:217], v[88:91]
	v_mfma_f32_16x16x32_bf16 v[80:83], v[182:185], v[222:225], v[80:83]
	v_mfma_f32_16x16x32_bf16 v[72:75], v[190:193], v[222:225], v[72:75]
	s_barrier
	s_add_i32 s69, 0, 0x14000
	s_add_i32 s21, s21, s43
	v_add_u32_e32 v138, s69, v155
	s_mov_b32 m0, s21
	ds_read_b128 v[226:229], v138
	ds_read_b128 v[230:233], v138 offset:1024
	ds_read_b128 v[234:237], v138 offset:2048
	ds_read_b128 v[238:241], v138 offset:3072
	global_load_lds_dwordx4 v136, s[38:39]
	s_add_i32 m0, s21, 0x2000
	v_mov_b32_e32 v147, v137
	global_load_lds_dwordx4 v146, s[38:39]
	v_lshl_add_u64 v[138:139], s[38:39], 0, v[136:137]
	v_lshl_add_u64 v[140:141], s[38:39], 0, v[146:147]
	s_mov_b32 m0, s48
	v_lshl_add_u64 v[242:243], s[40:41], 0, v[150:151]
	s_barrier
	s_waitcnt lgkmcnt(0)
	v_mfma_f32_16x16x32_bf16 v[116:119], v[226:229], v[194:197], v[116:119]
	v_mfma_f32_16x16x32_bf16 v[108:111], v[234:237], v[194:197], v[108:111]
	v_mfma_f32_16x16x32_bf16 v[100:103], v[226:229], v[202:205], v[100:103]
	v_mfma_f32_16x16x32_bf16 v[92:95], v[234:237], v[202:205], v[92:95]
	v_mfma_f32_16x16x32_bf16 v[84:87], v[226:229], v[210:213], v[84:87]
	v_mfma_f32_16x16x32_bf16 v[76:79], v[234:237], v[210:213], v[76:79]
	v_mfma_f32_16x16x32_bf16 v[68:71], v[226:229], v[218:221], v[68:71]
	v_mfma_f32_16x16x32_bf16 v[64:67], v[234:237], v[218:221], v[64:67]
	v_mfma_f32_16x16x32_bf16 v[116:119], v[230:233], v[198:201], v[116:119]
	v_mfma_f32_16x16x32_bf16 v[108:111], v[238:241], v[198:201], v[108:111]
	v_mfma_f32_16x16x32_bf16 v[100:103], v[230:233], v[206:209], v[100:103]
	v_mfma_f32_16x16x32_bf16 v[92:95], v[238:241], v[206:209], v[92:95]
	v_mfma_f32_16x16x32_bf16 v[84:87], v[230:233], v[214:217], v[84:87]
	v_mfma_f32_16x16x32_bf16 v[76:79], v[238:241], v[214:217], v[76:79]
	v_mfma_f32_16x16x32_bf16 v[68:71], v[230:233], v[222:225], v[68:71]
	v_mfma_f32_16x16x32_bf16 v[64:67], v[238:241], v[222:225], v[64:67]
	s_barrier
	ds_read_b128 v[194:197], v143 offset:16384
	ds_read_b128 v[198:201], v143 offset:17408
	ds_read_b128 v[202:205], v143 offset:18432
	ds_read_b128 v[206:209], v143 offset:19456
	ds_read_b128 v[210:213], v143 offset:20480
	ds_read_b128 v[214:217], v143 offset:21504
	ds_read_b128 v[218:221], v143 offset:22528
	ds_read_b128 v[222:225], v143 offset:23552
	global_load_lds_dwordx4 v[242:243], off
	v_lshl_add_u64 v[244:245], s[40:41], 0, v[148:149]
	s_mov_b32 m0, s49
	s_nop 0
	global_load_lds_dwordx4 v[244:245], off
	s_barrier
	s_waitcnt lgkmcnt(0)
	v_mfma_f32_16x16x32_bf16 v[60:63], v[158:161], v[194:197], v[60:63]
	v_mfma_f32_16x16x32_bf16 v[56:59], v[186:189], v[194:197], v[56:59]
	v_mfma_f32_16x16x32_bf16 v[44:47], v[158:161], v[202:205], v[44:47]
	v_mfma_f32_16x16x32_bf16 v[40:43], v[186:189], v[202:205], v[40:43]
	v_mfma_f32_16x16x32_bf16 v[28:31], v[158:161], v[210:213], v[28:31]
	v_mfma_f32_16x16x32_bf16 v[24:27], v[186:189], v[210:213], v[24:27]
	v_mfma_f32_16x16x32_bf16 v[12:15], v[158:161], v[218:221], v[12:15]
	v_mfma_f32_16x16x32_bf16 v[8:11], v[186:189], v[218:221], v[8:11]
	v_mfma_f32_16x16x32_bf16 v[60:63], v[182:185], v[198:201], v[60:63]
	v_mfma_f32_16x16x32_bf16 v[56:59], v[190:193], v[198:201], v[56:59]
	v_mfma_f32_16x16x32_bf16 v[44:47], v[182:185], v[206:209], v[44:47]
	v_mfma_f32_16x16x32_bf16 v[40:43], v[190:193], v[206:209], v[40:43]
	v_mfma_f32_16x16x32_bf16 v[28:31], v[182:185], v[214:217], v[28:31]
	v_mfma_f32_16x16x32_bf16 v[24:27], v[190:193], v[214:217], v[24:27]
	v_mfma_f32_16x16x32_bf16 v[12:15], v[182:185], v[222:225], v[12:15]
	v_mfma_f32_16x16x32_bf16 v[8:11], v[190:193], v[222:225], v[8:11]
	s_barrier
	s_add_u32 s70, s38, 0x80000
	s_addc_u32 s71, s39, 0
	s_add_i32 s21, s69, s43
	s_mov_b32 m0, s21
	s_nop 0
	global_load_lds_dwordx4 v136, s[70:71]
	s_add_i32 m0, s21, 0x2000
	s_nop 0
	global_load_lds_dwordx4 v146, s[70:71]
	s_add_i32 s21, 0, 0x18000
	v_add_u32_e32 v147, s21, v155
	s_waitcnt vmcnt(6)
	s_barrier
; #define PG8_STAGE(bufoff, gbase, v0, v1) do { \
;         __builtin_amdgcn_global_load_lds((const unsigned*)((const char*)(gbase) + (v0)), (LAS unsigned*)(lds + (bufoff) + ldsw), 16, 0, 0); \
;         __builtin_amdgcn_global_load_lds((const unsigned*)((const char*)(gbase) + (v1)), (LAS unsigned*)(lds + (bufoff) + ldsw + 8192), 16, 0, 0); } while (0)
; #define PG8_LDA(dst, b, h) do { _Pragma("unroll") for (int m = 0; m < 4; ++m) _Pragma("unroll") for (int k = 0; k < 2; ++k) dst[m][k] = *(const LAS bf16x8*)(lds + PG8_SA(b, h) + aoff + m * 2048 + k * 1024); } while (0)
; #define PG8_LDB(dst, b, h) do { _Pragma("unroll") for (int n = 0; n < 2; ++n) _Pragma("unroll") for (int k = 0; k < 2; ++k) dst[n][k] = *(const LAS bf16x8*)(lds + PG8_SB(b, h) + boff + n * 2048 + k * 1024); } while (0)
; #define PG8_MMA(ai, bj, At, Bt) do { __builtin_amdgcn_s_setprio(1); _Pragma("unroll") for (int m = 0; m < 4; ++m) _Pragma("unroll") for (int n = 0; n < 2; ++n) _Pragma("unroll") for (int k = 0; k < 2; ++k) \
;         acc[ai][bj][m][n] = __builtin_amdgcn_mfma_f32_16x16x32_bf16(Bt[n][k], At[m][k], acc[ai][bj][m][n], 0, 0, 0); __builtin_amdgcn_s_setprio(0); } while (0)
; #define PG8_WAIT_V(n) asm volatile("s_waitcnt vmcnt(" #n ")" ::: "memory")
; #define PG8_WAIT_L(n) asm volatile("s_waitcnt lgkmcnt(" #n ")" ::: "memory")
; #define PG8_BAR __builtin_amdgcn_s_barrier()
; #define PG8_SCHED __builtin_amdgcn_sched_barrier(0)
; template <class Epi, class Sched>
; __device__ __forceinline__ void gemm_phase(LAS unsigned char* lds, const Sched& S, const Epi& E) {
;     ...
;             PG8_WAIT_V(6); PG8_BAR; PG8_MMA(1, 1, At, B1); PG8_BAR;
;             PG8_LDB(B0, 1, 0); PG8_SCHED; PG8_LDA(At, 1, 0); PG8_STAGE(PG8_SA(0, 1), a2 + xhA, xA0, xA1);
;             PG8_WAIT_L(8); PG8_BAR; PG8_WAIT_L(0); PG8_MMA(0, 0, At, B0); PG8_BAR; PG8_SCHED;
;             PG8_LDB(B1, 1, 1); PG8_STAGE(PG8_SB(1, 0), b3, xB0, xB1);
;             PG8_BAR; PG8_WAIT_L(0); PG8_MMA(0, 1, At, B1); PG8_BAR;
	v_mfma_f32_16x16x32_bf16 v[52:55], v[226:229], v[194:197], v[52:55]
	v_mfma_f32_16x16x32_bf16 v[48:51], v[234:237], v[194:197], v[48:51]
	v_mfma_f32_16x16x32_bf16 v[36:39], v[226:229], v[202:205], v[36:39]
	v_mfma_f32_16x16x32_bf16 v[32:35], v[234:237], v[202:205], v[32:35]
	v_mfma_f32_16x16x32_bf16 v[20:23], v[226:229], v[210:213], v[20:23]
	v_mfma_f32_16x16x32_bf16 v[16:19], v[234:237], v[210:213], v[16:19]
	v_mfma_f32_16x16x32_bf16 v[4:7], v[226:229], v[218:221], v[4:7]
	v_mfma_f32_16x16x32_bf16 v[0:3], v[234:237], v[218:221], v[0:3]
	v_mfma_f32_16x16x32_bf16 v[52:55], v[230:233], v[198:201], v[52:55]
	v_mfma_f32_16x16x32_bf16 v[48:51], v[238:241], v[198:201], v[48:51]
	v_mfma_f32_16x16x32_bf16 v[36:39], v[230:233], v[206:209], v[36:39]
	v_mfma_f32_16x16x32_bf16 v[32:35], v[238:241], v[206:209], v[32:35]
	v_mfma_f32_16x16x32_bf16 v[20:23], v[230:233], v[214:217], v[20:23]
	v_mfma_f32_16x16x32_bf16 v[16:19], v[238:241], v[214:217], v[16:19]
	v_mfma_f32_16x16x32_bf16 v[4:7], v[230:233], v[222:225], v[4:7]
	v_mfma_f32_16x16x32_bf16 v[0:3], v[238:241], v[222:225], v[0:3]
	s_barrier
	ds_read_b128 v[158:161], v147
	ds_read_b128 v[182:185], v147 offset:1024
	ds_read_b128 v[186:189], v147 offset:2048
	ds_read_b128 v[190:193], v147 offset:3072
	s_add_u32 s40, s40, 0x80000
	s_addc_u32 s41, s41, 0
	s_mov_b32 m0, s50
	v_lshl_add_u64 v[150:151], s[40:41], 0, v[150:151]
	ds_read_b128 v[194:197], v143 offset:32768
	ds_read_b128 v[198:201], v143 offset:33792
	ds_read_b128 v[202:205], v143 offset:34816
	ds_read_b128 v[206:209], v143 offset:35840
	ds_read_b128 v[210:213], v143 offset:36864
	ds_read_b128 v[214:217], v143 offset:37888
	ds_read_b128 v[218:221], v143 offset:38912
	ds_read_b128 v[222:225], v143 offset:39936
	global_load_lds_dwordx4 v[150:151], off
	v_lshl_add_u64 v[148:149], s[40:41], 0, v[148:149]
	s_mov_b32 m0, s51
	s_nop 0
	global_load_lds_dwordx4 v[148:149], off
	s_waitcnt lgkmcnt(8)
	s_barrier
	s_waitcnt lgkmcnt(0)
	v_mfma_f32_16x16x32_bf16 v[124:127], v[158:161], v[194:197], v[124:127]
	v_mfma_f32_16x16x32_bf16 v[120:123], v[186:189], v[194:197], v[120:123]
	v_mfma_f32_16x16x32_bf16 v[112:115], v[158:161], v[202:205], v[112:115]
	v_mfma_f32_16x16x32_bf16 v[104:107], v[186:189], v[202:205], v[104:107]
	v_mfma_f32_16x16x32_bf16 v[96:99], v[158:161], v[210:213], v[96:99]
	v_mfma_f32_16x16x32_bf16 v[88:91], v[186:189], v[210:213], v[88:91]
	v_mfma_f32_16x16x32_bf16 v[80:83], v[158:161], v[218:221], v[80:83]
	v_mfma_f32_16x16x32_bf16 v[72:75], v[186:189], v[218:221], v[72:75]
	v_mfma_f32_16x16x32_bf16 v[124:127], v[182:185], v[198:201], v[124:127]
	v_mfma_f32_16x16x32_bf16 v[120:123], v[190:193], v[198:201], v[120:123]
	v_mfma_f32_16x16x32_bf16 v[112:115], v[182:185], v[206:209], v[112:115]
	v_mfma_f32_16x16x32_bf16 v[104:107], v[190:193], v[206:209], v[104:107]
	v_mfma_f32_16x16x32_bf16 v[96:99], v[182:185], v[214:217], v[96:99]
	v_mfma_f32_16x16x32_bf16 v[88:91], v[190:193], v[214:217], v[88:91]
	v_mfma_f32_16x16x32_bf16 v[80:83], v[182:185], v[222:225], v[80:83]
	v_mfma_f32_16x16x32_bf16 v[72:75], v[190:193], v[222:225], v[72:75]
	s_barrier
	s_add_i32 s40, 0, 0x1c000
	s_add_i32 s21, s21, s43
	v_add_u32_e32 v147, s40, v155
	v_lshl_add_u64 v[138:139], v[138:139], 0, s[44:45]
	s_mov_b32 m0, s21
	ds_read_b128 v[148:151], v147
	ds_read_b128 v[226:229], v147 offset:1024
	ds_read_b128 v[230:233], v147 offset:2048
	ds_read_b128 v[234:237], v147 offset:3072
	global_load_lds_dwordx4 v[138:139], off
	v_lshl_add_u64 v[138:139], v[140:141], 0, s[44:45]
	s_add_i32 m0, s21, 0x2000
	s_nop 0
	global_load_lds_dwordx4 v[138:139], off
	s_mov_b32 m0, s64
	v_lshl_add_u64 v[138:139], v[242:243], 0, s[44:45]
	s_barrier
; #define PG8_STAGE(bufoff, gbase, v0, v1) do { \
;         __builtin_amdgcn_global_load_lds((const unsigned*)((const char*)(gbase) + (v0)), (LAS unsigned*)(lds + (bufoff) + ldsw), 16, 0, 0); \
;         __builtin_amdgcn_global_load_lds((const unsigned*)((const char*)(gbase) + (v1)), (LAS unsigned*)(lds + (bufoff) + ldsw + 8192), 16, 0, 0); } while (0)
; #define PG8_LDA(dst, b, h) do { _Pragma("unroll") for (int m = 0; m < 4; ++m) _Pragma("unroll") for (int k = 0; k < 2; ++k) dst[m][k] = *(const LAS bf16x8*)(lds + PG8_SA(b, h) + aoff + m * 2048 + k * 1024); } while (0)
; #define PG8_MMA(ai, bj, At, Bt) do { __builtin_amdgcn_s_setprio(1); _Pragma("unroll") for (int m = 0; m < 4; ++m) _Pragma("unroll") for (int n = 0; n < 2; ++n) _Pragma("unroll") for (int k = 0; k < 2; ++k) \
;         acc[ai][bj][m][n] = __builtin_amdgcn_mfma_f32_16x16x32_bf16(Bt[n][k], At[m][k], acc[ai][bj][m][n], 0, 0, 0); __builtin_amdgcn_s_setprio(0); } while (0)
; #define PG8_WAIT_V(n) asm volatile("s_waitcnt vmcnt(" #n ")" ::: "memory")
; #define PG8_WAIT_L(n) asm volatile("s_waitcnt lgkmcnt(" #n ")" ::: "memory")
; #define PG8_BAR __builtin_amdgcn_s_barrier()
; #define PG8_SCHED __builtin_amdgcn_sched_barrier(0)
; template <class Epi, class Sched>
; __device__ __forceinline__ void gemm_phase(LAS unsigned char* lds, const Sched& S, const Epi& E) {
;     ...
;         for (int t = 0; t < nt; t += 2) {
;             const bool last = (t == nt - 2);
;             const char* a1 = cA + (size_t)(t + 1) * kstep;
;             const char* a2 = last ? nA : cA + (size_t)(t + 2) * kstep; const char* b2 = last ? nB : cB + (size_t)(t + 2) * kstep;
;             const char* a3 = a2 + kstep; const char* b3 = b2 + kstep;
;             const unsigned xA0 = last ? nvA0 : vA0, xA1 = last ? nvA1 : vA1, xB0 = last ? nvB0 : vB0, xB1 = last ? nvB1 : vB1;
;     ...
;             PG8_BAR; PG8_WAIT_L(0); PG8_MMA(0, 1, At, B1); PG8_BAR;
;             PG8_LDA(At, 1, 1); PG8_STAGE(PG8_SA(1, 0), a3, xA0, xA1);
;             PG8_BAR; PG8_WAIT_L(0); PG8_MMA(1, 0, At, B0); PG8_BAR; PG8_SCHED;
;             PG8_STAGE(PG8_SB(1, 1), b3 + xhB, xB0, xB1);
;             PG8_WAIT_V(6); PG8_BAR; PG8_MMA(1, 1, At, B1); PG8_BAR;
	s_waitcnt lgkmcnt(0)
	v_mfma_f32_16x16x32_bf16 v[116:119], v[148:151], v[194:197], v[116:119]
	v_mfma_f32_16x16x32_bf16 v[108:111], v[230:233], v[194:197], v[108:111]
	v_mfma_f32_16x16x32_bf16 v[100:103], v[148:151], v[202:205], v[100:103]
	v_mfma_f32_16x16x32_bf16 v[92:95], v[230:233], v[202:205], v[92:95]
	v_mfma_f32_16x16x32_bf16 v[84:87], v[148:151], v[210:213], v[84:87]
	v_mfma_f32_16x16x32_bf16 v[76:79], v[230:233], v[210:213], v[76:79]
	v_mfma_f32_16x16x32_bf16 v[68:71], v[148:151], v[218:221], v[68:71]
	v_mfma_f32_16x16x32_bf16 v[64:67], v[230:233], v[218:221], v[64:67]
	v_mfma_f32_16x16x32_bf16 v[116:119], v[226:229], v[198:201], v[116:119]
	v_mfma_f32_16x16x32_bf16 v[108:111], v[234:237], v[198:201], v[108:111]
	v_mfma_f32_16x16x32_bf16 v[100:103], v[226:229], v[206:209], v[100:103]
	v_mfma_f32_16x16x32_bf16 v[92:95], v[234:237], v[206:209], v[92:95]
	v_mfma_f32_16x16x32_bf16 v[84:87], v[226:229], v[214:217], v[84:87]
	v_mfma_f32_16x16x32_bf16 v[76:79], v[234:237], v[214:217], v[76:79]
	v_mfma_f32_16x16x32_bf16 v[68:71], v[226:229], v[222:225], v[68:71]
	v_mfma_f32_16x16x32_bf16 v[64:67], v[234:237], v[222:225], v[64:67]
	s_barrier
	ds_read_b128 v[194:197], v143 offset:49152
	ds_read_b128 v[198:201], v143 offset:50176
	ds_read_b128 v[202:205], v143 offset:51200
	ds_read_b128 v[206:209], v143 offset:52224
	ds_read_b128 v[210:213], v143 offset:53248
	ds_read_b128 v[214:217], v143 offset:54272
	ds_read_b128 v[218:221], v143 offset:55296
	ds_read_b128 v[222:225], v143 offset:56320
	global_load_lds_dwordx4 v[138:139], off
	v_lshl_add_u64 v[138:139], v[244:245], 0, s[44:45]
	s_mov_b32 m0, s65
	s_nop 0
	global_load_lds_dwordx4 v[138:139], off
	s_barrier
	s_waitcnt lgkmcnt(0)
	v_mfma_f32_16x16x32_bf16 v[60:63], v[158:161], v[194:197], v[60:63]
	v_mfma_f32_16x16x32_bf16 v[56:59], v[186:189], v[194:197], v[56:59]
	v_mfma_f32_16x16x32_bf16 v[44:47], v[158:161], v[202:205], v[44:47]
	v_mfma_f32_16x16x32_bf16 v[40:43], v[186:189], v[202:205], v[40:43]
	v_mfma_f32_16x16x32_bf16 v[28:31], v[158:161], v[210:213], v[28:31]
	v_mfma_f32_16x16x32_bf16 v[24:27], v[186:189], v[210:213], v[24:27]
	v_mfma_f32_16x16x32_bf16 v[12:15], v[158:161], v[218:221], v[12:15]
	v_mfma_f32_16x16x32_bf16 v[8:11], v[186:189], v[218:221], v[8:11]
	v_mfma_f32_16x16x32_bf16 v[60:63], v[182:185], v[198:201], v[60:63]
	v_mfma_f32_16x16x32_bf16 v[56:59], v[190:193], v[198:201], v[56:59]
	v_mfma_f32_16x16x32_bf16 v[44:47], v[182:185], v[206:209], v[44:47]
	v_mfma_f32_16x16x32_bf16 v[40:43], v[190:193], v[206:209], v[40:43]
	v_mfma_f32_16x16x32_bf16 v[28:31], v[182:185], v[214:217], v[28:31]
	v_mfma_f32_16x16x32_bf16 v[24:27], v[190:193], v[214:217], v[24:27]
	v_mfma_f32_16x16x32_bf16 v[12:15], v[182:185], v[222:225], v[12:15]
	v_mfma_f32_16x16x32_bf16 v[8:11], v[190:193], v[222:225], v[8:11]
	s_barrier
	s_add_u32 s38, s38, 0x80080
	s_addc_u32 s39, s39, 0
	s_add_i32 s21, s40, s43
	s_mov_b32 m0, s21
	s_nop 0
	global_load_lds_dwordx4 v136, s[38:39]
	s_add_i32 m0, s21, 0x2000
	s_nop 0
	global_load_lds_dwordx4 v146, s[38:39]
	s_waitcnt vmcnt(6)
	s_barrier
	v_mfma_f32_16x16x32_bf16 v[52:55], v[148:151], v[194:197], v[52:55]
	v_mfma_f32_16x16x32_bf16 v[48:51], v[230:233], v[194:197], v[48:51]
	v_mfma_f32_16x16x32_bf16 v[36:39], v[148:151], v[202:205], v[36:39]
	v_mfma_f32_16x16x32_bf16 v[32:35], v[230:233], v[202:205], v[32:35]
	v_mfma_f32_16x16x32_bf16 v[20:23], v[148:151], v[210:213], v[20:23]
	v_mfma_f32_16x16x32_bf16 v[16:19], v[230:233], v[210:213], v[16:19]
	v_mfma_f32_16x16x32_bf16 v[4:7], v[148:151], v[218:221], v[4:7]
	v_mfma_f32_16x16x32_bf16 v[0:3], v[230:233], v[218:221], v[0:3]
	v_mfma_f32_16x16x32_bf16 v[52:55], v[226:229], v[198:201], v[52:55]
	v_mfma_f32_16x16x32_bf16 v[48:51], v[234:237], v[198:201], v[48:51]
	v_mfma_f32_16x16x32_bf16 v[36:39], v[226:229], v[206:209], v[36:39]
	v_mfma_f32_16x16x32_bf16 v[32:35], v[234:237], v[206:209], v[32:35]
	v_mfma_f32_16x16x32_bf16 v[20:23], v[226:229], v[214:217], v[20:23]
	v_mfma_f32_16x16x32_bf16 v[16:19], v[234:237], v[214:217], v[16:19]
	v_mfma_f32_16x16x32_bf16 v[4:7], v[226:229], v[222:225], v[4:7]
	v_mfma_f32_16x16x32_bf16 v[0:3], v[234:237], v[222:225], v[0:3]
	s_add_i32 s15, s15, 2
	s_add_u32 s26, s26, 0x100
	s_addc_u32 s27, s27, 0
	s_add_u32 s34, s34, 0x100
	s_addc_u32 s35, s35, 0
	s_cmp_gt_u32 s15, 29
	s_cbranch_scc1 .Lrot_exit_3
	s_cmp_eq_u32 s15, 28
	s_cselect_b64 s[40:41], -1, 0
	s_and_b64 vcc, exec, s[40:41]
	v_mov_b64_e32 v[148:149], v[130:131]
	v_mov_b64_e32 v[150:151], v[128:129]
	v_mov_b32_e32 v146, v156
	v_mov_b32_e32 v136, v145
	s_mov_b64 s[38:39], s[24:25]
	s_cbranch_vccnz .Lrot_join_3
	v_mov_b64_e32 v[148:149], v[134:135]
	v_mov_b64_e32 v[150:151], v[132:133]
	v_mov_b32_e32 v146, v142
	v_mov_b32_e32 v136, v144
	s_mov_b64 s[38:39], s[34:35]

; #define PG8_STAGE(bufoff, gbase, v0, v1) do { \
;         __builtin_amdgcn_global_load_lds((const unsigned*)((const char*)(gbase) + (v0)), (LAS unsigned*)(lds + (bufoff) + ldsw), 16, 0, 0); \
;         __builtin_amdgcn_global_load_lds((const unsigned*)((const char*)(gbase) + (v1)), (LAS unsigned*)(lds + (bufoff) + ldsw + 8192), 16, 0, 0); } while (0)
; #define PG8_LDA(dst, b, h) do { _Pragma("unroll") for (int m = 0; m < 4; ++m) _Pragma("unroll") for (int k = 0; k < 2; ++k) dst[m][k] = *(const LAS bf16x8*)(lds + PG8_SA(b, h) + aoff + m * 2048 + k * 1024); } while (0)
; #define PG8_LDB(dst, b, h) do { _Pragma("unroll") for (int n = 0; n < 2; ++n) _Pragma("unroll") for (int k = 0; k < 2; ++k) dst[n][k] = *(const LAS bf16x8*)(lds + PG8_SB(b, h) + boff + n * 2048 + k * 1024); } while (0)
; #define PG8_MMA(ai, bj, At, Bt) do { __builtin_amdgcn_s_setprio(1); _Pragma("unroll") for (int m = 0; m < 4; ++m) _Pragma("unroll") for (int n = 0; n < 2; ++n) _Pragma("unroll") for (int k = 0; k < 2; ++k) \
;         acc[ai][bj][m][n] = __builtin_amdgcn_mfma_f32_16x16x32_bf16(Bt[n][k], At[m][k], acc[ai][bj][m][n], 0, 0, 0); __builtin_amdgcn_s_setprio(0); } while (0)
; #define PG8_WAIT_V(n) asm volatile("s_waitcnt vmcnt(" #n ")" ::: "memory")
; #define PG8_WAIT_L(n) asm volatile("s_waitcnt lgkmcnt(" #n ")" ::: "memory")
; #define PG8_BAR __builtin_amdgcn_s_barrier()
; #define PG8_SCHED __builtin_amdgcn_sched_barrier(0)
; template <class Epi, class Sched>
; __device__ __forceinline__ void gemm_phase(LAS unsigned char* lds, const Sched& S, const Epi& E) {
;     ...
;             PG8_LDB(B0, 0, 0); PG8_SCHED; PG8_LDA(At, 0, 0); PG8_STAGE(PG8_SA(1, 1), a1 + hA, vA0, vA1);
;             PG8_WAIT_L(8); PG8_BAR; PG8_WAIT_L(0); PG8_MMA(0, 0, At, B0); PG8_BAR; PG8_SCHED;
;             PG8_LDB(B1, 0, 1); PG8_STAGE(PG8_SB(0, 0), b2, xB0, xB1);
;             PG8_BAR; PG8_WAIT_L(0); PG8_MMA(0, 1, At, B1); PG8_BAR;
;             PG8_LDA(At, 0, 1); PG8_STAGE(PG8_SA(0, 0), a2, xA0, xA1);
;             PG8_BAR; PG8_WAIT_L(0); PG8_MMA(1, 0, At, B0); PG8_BAR; PG8_SCHED;
;             PG8_STAGE(PG8_SB(0, 1), b2 + xhB, xB0, xB1);
;             PG8_WAIT_V(6); PG8_BAR; PG8_MMA(1, 1, At, B1); PG8_BAR;
;             PG8_LDB(B0, 1, 0); PG8_SCHED; PG8_LDA(At, 1, 0); PG8_STAGE(PG8_SA(0, 1), a2 + xhA, xA0, xA1);
.Lrot_body_4:
	ds_read_b128 v[150:153], v138
	ds_read_b128 v[154:157], v138 offset:1024
	ds_read_b128 v[158:161], v138 offset:2048
	ds_read_b128 v[182:185], v138 offset:3072
	v_lshl_add_u64 v[138:139], s[24:25], 0, v[136:137]
	s_add_i32 m0, s49, 0xc000
	ds_read_b128 v[186:189], v148
	ds_read_b128 v[190:193], v148 offset:1024
	ds_read_b128 v[194:197], v148 offset:2048
	ds_read_b128 v[198:201], v148 offset:3072
	ds_read_b128 v[202:205], v148 offset:4096
	ds_read_b128 v[206:209], v148 offset:5120
	ds_read_b128 v[210:213], v148 offset:6144
	ds_read_b128 v[214:217], v148 offset:7168
	global_load_lds_dwordx4 v[138:139], off
	v_lshl_add_u64 v[138:139], s[24:25], 0, v[132:133]
	s_add_i32 m0, s49, 0xe000
	s_nop 0
	global_load_lds_dwordx4 v[138:139], off
	s_waitcnt lgkmcnt(8)
	s_barrier
	s_waitcnt lgkmcnt(0)
	v_mfma_f32_16x16x32_bf16 v[124:127], v[150:153], v[186:189], v[124:127]
	v_mfma_f32_16x16x32_bf16 v[120:123], v[158:161], v[186:189], v[120:123]
	v_mfma_f32_16x16x32_bf16 v[108:111], v[150:153], v[194:197], v[108:111]
	v_mfma_f32_16x16x32_bf16 v[104:107], v[158:161], v[194:197], v[104:107]
	v_mfma_f32_16x16x32_bf16 v[100:103], v[150:153], v[202:205], v[100:103]
	v_mfma_f32_16x16x32_bf16 v[96:99], v[158:161], v[202:205], v[96:99]
	v_mfma_f32_16x16x32_bf16 v[84:87], v[150:153], v[210:213], v[84:87]
	v_mfma_f32_16x16x32_bf16 v[80:83], v[158:161], v[210:213], v[80:83]
	v_mfma_f32_16x16x32_bf16 v[124:127], v[154:157], v[190:193], v[124:127]
	v_mfma_f32_16x16x32_bf16 v[120:123], v[182:185], v[190:193], v[120:123]
	v_mfma_f32_16x16x32_bf16 v[108:111], v[154:157], v[198:201], v[108:111]
	v_mfma_f32_16x16x32_bf16 v[104:107], v[182:185], v[198:201], v[104:107]
	v_mfma_f32_16x16x32_bf16 v[100:103], v[154:157], v[206:209], v[100:103]
	v_mfma_f32_16x16x32_bf16 v[96:99], v[182:185], v[206:209], v[96:99]
	v_mfma_f32_16x16x32_bf16 v[84:87], v[154:157], v[214:217], v[84:87]
	v_mfma_f32_16x16x32_bf16 v[80:83], v[182:185], v[214:217], v[80:83]
	s_barrier
	s_add_i32 s82, 0, 0x14000
	v_add_u32_e32 v138, s82, v147
	s_add_i32 s15, s15, s48
	ds_read_b128 v[218:221], v138
	ds_read_b128 v[222:225], v138 offset:1024
	ds_read_b128 v[226:229], v138 offset:2048
	ds_read_b128 v[230:233], v138 offset:3072
	v_lshl_add_u64 v[138:139], s[34:35], 0, v[142:143]
	s_mov_b32 m0, s15
	v_lshl_add_u64 v[140:141], s[34:35], 0, v[134:135]
	global_load_lds_dwordx4 v[138:139], off
	s_add_i32 m0, s15, 0x2000
	s_nop 0
	global_load_lds_dwordx4 v[140:141], off
	s_mov_b32 m0, s49
	v_lshl_add_u64 v[234:235], s[38:39], 0, v[142:143]
	s_barrier
	s_waitcnt lgkmcnt(0)
	v_mfma_f32_16x16x32_bf16 v[116:119], v[218:221], v[186:189], v[116:119]
	v_mfma_f32_16x16x32_bf16 v[112:115], v[226:229], v[186:189], v[112:115]
	v_mfma_f32_16x16x32_bf16 v[92:95], v[218:221], v[194:197], v[92:95]
	v_mfma_f32_16x16x32_bf16 v[88:91], v[226:229], v[194:197], v[88:91]
	v_mfma_f32_16x16x32_bf16 v[76:79], v[218:221], v[202:205], v[76:79]
	v_mfma_f32_16x16x32_bf16 v[72:75], v[226:229], v[202:205], v[72:75]
	v_mfma_f32_16x16x32_bf16 v[68:71], v[218:221], v[210:213], v[68:71]
	v_mfma_f32_16x16x32_bf16 v[64:67], v[226:229], v[210:213], v[64:67]
	v_mfma_f32_16x16x32_bf16 v[116:119], v[222:225], v[190:193], v[116:119]
	v_mfma_f32_16x16x32_bf16 v[112:115], v[230:233], v[190:193], v[112:115]
	v_mfma_f32_16x16x32_bf16 v[92:95], v[222:225], v[198:201], v[92:95]
	v_mfma_f32_16x16x32_bf16 v[88:91], v[230:233], v[198:201], v[88:91]
	v_mfma_f32_16x16x32_bf16 v[76:79], v[222:225], v[206:209], v[76:79]
	v_mfma_f32_16x16x32_bf16 v[72:75], v[230:233], v[206:209], v[72:75]
	v_mfma_f32_16x16x32_bf16 v[68:71], v[222:225], v[214:217], v[68:71]
	v_mfma_f32_16x16x32_bf16 v[64:67], v[230:233], v[214:217], v[64:67]
	s_barrier
	ds_read_b128 v[186:189], v148 offset:16384
	ds_read_b128 v[190:193], v148 offset:17408
	ds_read_b128 v[194:197], v148 offset:18432
	ds_read_b128 v[198:201], v148 offset:19456
	ds_read_b128 v[202:205], v148 offset:20480
	ds_read_b128 v[206:209], v148 offset:21504
	ds_read_b128 v[210:213], v148 offset:22528
	ds_read_b128 v[214:217], v148 offset:23552
	global_load_lds_dwordx4 v[234:235], off
	v_lshl_add_u64 v[236:237], s[38:39], 0, v[134:135]
	s_mov_b32 m0, s50
	s_nop 0
	global_load_lds_dwordx4 v[236:237], off
	s_barrier
	s_waitcnt lgkmcnt(0)
	v_mfma_f32_16x16x32_bf16 v[60:63], v[150:153], v[186:189], v[60:63]
	v_mfma_f32_16x16x32_bf16 v[56:59], v[158:161], v[186:189], v[56:59]
	v_mfma_f32_16x16x32_bf16 v[44:47], v[150:153], v[194:197], v[44:47]
	v_mfma_f32_16x16x32_bf16 v[40:43], v[158:161], v[194:197], v[40:43]
	v_mfma_f32_16x16x32_bf16 v[28:31], v[150:153], v[202:205], v[28:31]
	v_mfma_f32_16x16x32_bf16 v[24:27], v[158:161], v[202:205], v[24:27]
	v_mfma_f32_16x16x32_bf16 v[12:15], v[150:153], v[210:213], v[12:15]
	v_mfma_f32_16x16x32_bf16 v[8:11], v[158:161], v[210:213], v[8:11]
	v_mfma_f32_16x16x32_bf16 v[60:63], v[154:157], v[190:193], v[60:63]
	v_mfma_f32_16x16x32_bf16 v[56:59], v[182:185], v[190:193], v[56:59]
	v_mfma_f32_16x16x32_bf16 v[44:47], v[154:157], v[198:201], v[44:47]
	v_mfma_f32_16x16x32_bf16 v[40:43], v[182:185], v[198:201], v[40:43]
	v_mfma_f32_16x16x32_bf16 v[28:31], v[154:157], v[206:209], v[28:31]
	v_mfma_f32_16x16x32_bf16 v[24:27], v[182:185], v[206:209], v[24:27]
	v_mfma_f32_16x16x32_bf16 v[12:15], v[154:157], v[214:217], v[12:15]
	v_mfma_f32_16x16x32_bf16 v[8:11], v[182:185], v[214:217], v[8:11]
	s_barrier
	s_add_u32 s70, s34, 0x200000
	s_addc_u32 s71, s35, 0
	s_add_i32 s15, s82, s48
	v_lshl_add_u64 v[150:151], s[70:71], 0, v[142:143]
	s_mov_b32 m0, s15
	s_nop 0
	global_load_lds_dwordx4 v[150:151], off
	v_lshl_add_u64 v[150:151], s[70:71], 0, v[134:135]
	s_add_i32 m0, s15, 0x2000
	s_nop 0
	global_load_lds_dwordx4 v[150:151], off
	s_add_i32 s15, 0, 0x18000
	v_add_u32_e32 v149, s15, v147
	s_waitcnt vmcnt(6)
	s_barrier
; #define PG8_STAGE(bufoff, gbase, v0, v1) do { \
;         __builtin_amdgcn_global_load_lds((const unsigned*)((const char*)(gbase) + (v0)), (LAS unsigned*)(lds + (bufoff) + ldsw), 16, 0, 0); \
;         __builtin_amdgcn_global_load_lds((const unsigned*)((const char*)(gbase) + (v1)), (LAS unsigned*)(lds + (bufoff) + ldsw + 8192), 16, 0, 0); } while (0)
; #define PG8_LDA(dst, b, h) do { _Pragma("unroll") for (int m = 0; m < 4; ++m) _Pragma("unroll") for (int k = 0; k < 2; ++k) dst[m][k] = *(const LAS bf16x8*)(lds + PG8_SA(b, h) + aoff + m * 2048 + k * 1024); } while (0)
; #define PG8_LDB(dst, b, h) do { _Pragma("unroll") for (int n = 0; n < 2; ++n) _Pragma("unroll") for (int k = 0; k < 2; ++k) dst[n][k] = *(const LAS bf16x8*)(lds + PG8_SB(b, h) + boff + n * 2048 + k * 1024); } while (0)
; #define PG8_MMA(ai, bj, At, Bt) do { __builtin_amdgcn_s_setprio(1); _Pragma("unroll") for (int m = 0; m < 4; ++m) _Pragma("unroll") for (int n = 0; n < 2; ++n) _Pragma("unroll") for (int k = 0; k < 2; ++k) \
;         acc[ai][bj][m][n] = __builtin_amdgcn_mfma_f32_16x16x32_bf16(Bt[n][k], At[m][k], acc[ai][bj][m][n], 0, 0, 0); __builtin_amdgcn_s_setprio(0); } while (0)
; #define PG8_WAIT_V(n) asm volatile("s_waitcnt vmcnt(" #n ")" ::: "memory")
; #define PG8_WAIT_L(n) asm volatile("s_waitcnt lgkmcnt(" #n ")" ::: "memory")
; #define PG8_BAR __builtin_amdgcn_s_barrier()
; #define PG8_SCHED __builtin_amdgcn_sched_barrier(0)
; template <class Epi, class Sched>
; __device__ __forceinline__ void gemm_phase(LAS unsigned char* lds, const Sched& S, const Epi& E) {
;     ...
;             PG8_WAIT_V(6); PG8_BAR; PG8_MMA(1, 1, At, B1); PG8_BAR;
;             PG8_LDB(B0, 1, 0); PG8_SCHED; PG8_LDA(At, 1, 0); PG8_STAGE(PG8_SA(0, 1), a2 + xhA, xA0, xA1);
;             PG8_WAIT_L(8); PG8_BAR; PG8_WAIT_L(0); PG8_MMA(0, 0, At, B0); PG8_BAR; PG8_SCHED;
;             PG8_LDB(B1, 1, 1); PG8_STAGE(PG8_SB(1, 0), b3, xB0, xB1);
;             PG8_BAR; PG8_WAIT_L(0); PG8_MMA(0, 1, At, B1); PG8_BAR;
	v_mfma_f32_16x16x32_bf16 v[52:55], v[218:221], v[186:189], v[52:55]
	v_mfma_f32_16x16x32_bf16 v[48:51], v[226:229], v[186:189], v[48:51]
	v_mfma_f32_16x16x32_bf16 v[36:39], v[218:221], v[194:197], v[36:39]
	v_mfma_f32_16x16x32_bf16 v[32:35], v[226:229], v[194:197], v[32:35]
	v_mfma_f32_16x16x32_bf16 v[20:23], v[218:221], v[202:205], v[20:23]
	v_mfma_f32_16x16x32_bf16 v[16:19], v[226:229], v[202:205], v[16:19]
	v_mfma_f32_16x16x32_bf16 v[4:7], v[218:221], v[210:213], v[4:7]
	v_mfma_f32_16x16x32_bf16 v[0:3], v[226:229], v[210:213], v[0:3]
	v_mfma_f32_16x16x32_bf16 v[52:55], v[222:225], v[190:193], v[52:55]
	v_mfma_f32_16x16x32_bf16 v[48:51], v[230:233], v[190:193], v[48:51]
	v_mfma_f32_16x16x32_bf16 v[36:39], v[222:225], v[198:201], v[36:39]
	v_mfma_f32_16x16x32_bf16 v[32:35], v[230:233], v[198:201], v[32:35]
	v_mfma_f32_16x16x32_bf16 v[20:23], v[222:225], v[206:209], v[20:23]
	v_mfma_f32_16x16x32_bf16 v[16:19], v[230:233], v[206:209], v[16:19]
	v_mfma_f32_16x16x32_bf16 v[4:7], v[222:225], v[214:217], v[4:7]
	v_mfma_f32_16x16x32_bf16 v[0:3], v[230:233], v[214:217], v[0:3]
	s_barrier
	ds_read_b128 v[150:153], v149
	ds_read_b128 v[154:157], v149 offset:1024
	ds_read_b128 v[158:161], v149 offset:2048
	ds_read_b128 v[182:185], v149 offset:3072
	s_add_u32 s38, s38, 0x200000
	s_addc_u32 s39, s39, 0
	s_mov_b32 m0, s51
	v_lshl_add_u64 v[218:219], s[38:39], 0, v[142:143]
	ds_read_b128 v[186:189], v148 offset:32768
	ds_read_b128 v[190:193], v148 offset:33792
	ds_read_b128 v[194:197], v148 offset:34816
	ds_read_b128 v[198:201], v148 offset:35840
	ds_read_b128 v[202:205], v148 offset:36864
	ds_read_b128 v[206:209], v148 offset:37888
	ds_read_b128 v[210:213], v148 offset:38912
	ds_read_b128 v[214:217], v148 offset:39936
	global_load_lds_dwordx4 v[218:219], off
	v_lshl_add_u64 v[218:219], s[38:39], 0, v[134:135]
	s_mov_b32 m0, s54
	s_nop 0
	global_load_lds_dwordx4 v[218:219], off
	s_waitcnt lgkmcnt(8)
	s_barrier
	s_waitcnt lgkmcnt(0)
	v_mfma_f32_16x16x32_bf16 v[124:127], v[150:153], v[186:189], v[124:127]
	v_mfma_f32_16x16x32_bf16 v[120:123], v[158:161], v[186:189], v[120:123]
	v_mfma_f32_16x16x32_bf16 v[108:111], v[150:153], v[194:197], v[108:111]
	v_mfma_f32_16x16x32_bf16 v[104:107], v[158:161], v[194:197], v[104:107]
	v_mfma_f32_16x16x32_bf16 v[100:103], v[150:153], v[202:205], v[100:103]
	v_mfma_f32_16x16x32_bf16 v[96:99], v[158:161], v[202:205], v[96:99]
	v_mfma_f32_16x16x32_bf16 v[84:87], v[150:153], v[210:213], v[84:87]
	v_mfma_f32_16x16x32_bf16 v[80:83], v[158:161], v[210:213], v[80:83]
	v_mfma_f32_16x16x32_bf16 v[124:127], v[154:157], v[190:193], v[124:127]
	v_mfma_f32_16x16x32_bf16 v[120:123], v[182:185], v[190:193], v[120:123]
	v_mfma_f32_16x16x32_bf16 v[108:111], v[154:157], v[198:201], v[108:111]
	v_mfma_f32_16x16x32_bf16 v[104:107], v[182:185], v[198:201], v[104:107]
	v_mfma_f32_16x16x32_bf16 v[100:103], v[154:157], v[206:209], v[100:103]
	v_mfma_f32_16x16x32_bf16 v[96:99], v[182:185], v[206:209], v[96:99]
	v_mfma_f32_16x16x32_bf16 v[84:87], v[154:157], v[214:217], v[84:87]
	v_mfma_f32_16x16x32_bf16 v[80:83], v[182:185], v[214:217], v[80:83]
	s_barrier
	s_add_i32 s38, 0, 0x1c000
	s_add_i32 s15, s15, s48
	v_add_u32_e32 v149, s38, v147
	v_lshl_add_u64 v[138:139], v[138:139], 0, s[44:45]
	s_mov_b32 m0, s15
	ds_read_b128 v[218:221], v149
	ds_read_b128 v[222:225], v149 offset:1024
	ds_read_b128 v[226:229], v149 offset:2048
	ds_read_b128 v[230:233], v149 offset:3072
	global_load_lds_dwordx4 v[138:139], off
	v_lshl_add_u64 v[138:139], v[140:141], 0, s[44:45]
	s_add_i32 m0, s15, 0x2000
	s_nop 0
	global_load_lds_dwordx4 v[138:139], off
	s_mov_b32 m0, s65
	v_lshl_add_u64 v[138:139], v[234:235], 0, s[44:45]
	s_barrier
; #define PG8_STAGE(bufoff, gbase, v0, v1) do { \
;         __builtin_amdgcn_global_load_lds((const unsigned*)((const char*)(gbase) + (v0)), (LAS unsigned*)(lds + (bufoff) + ldsw), 16, 0, 0); \
;         __builtin_amdgcn_global_load_lds((const unsigned*)((const char*)(gbase) + (v1)), (LAS unsigned*)(lds + (bufoff) + ldsw + 8192), 16, 0, 0); } while (0)
; #define PG8_LDA(dst, b, h) do { _Pragma("unroll") for (int m = 0; m < 4; ++m) _Pragma("unroll") for (int k = 0; k < 2; ++k) dst[m][k] = *(const LAS bf16x8*)(lds + PG8_SA(b, h) + aoff + m * 2048 + k * 1024); } while (0)
; #define PG8_MMA(ai, bj, At, Bt) do { __builtin_amdgcn_s_setprio(1); _Pragma("unroll") for (int m = 0; m < 4; ++m) _Pragma("unroll") for (int n = 0; n < 2; ++n) _Pragma("unroll") for (int k = 0; k < 2; ++k) \
;         acc[ai][bj][m][n] = __builtin_amdgcn_mfma_f32_16x16x32_bf16(Bt[n][k], At[m][k], acc[ai][bj][m][n], 0, 0, 0); __builtin_amdgcn_s_setprio(0); } while (0)
; #define PG8_WAIT_V(n) asm volatile("s_waitcnt vmcnt(" #n ")" ::: "memory")
; #define PG8_WAIT_L(n) asm volatile("s_waitcnt lgkmcnt(" #n ")" ::: "memory")
; #define PG8_BAR __builtin_amdgcn_s_barrier()
; #define PG8_SCHED __builtin_amdgcn_sched_barrier(0)
; template <class Epi, class Sched>
; __device__ __forceinline__ void gemm_phase(LAS unsigned char* lds, const Sched& S, const Epi& E) {
;     ...
;         for (int t = 0; t < nt; t += 2) {
;             const bool last = (t == nt - 2);
;             const char* a1 = cA + (size_t)(t + 1) * kstep;
;             const char* a2 = last ? nA : cA + (size_t)(t + 2) * kstep; const char* b2 = last ? nB : cB + (size_t)(t + 2) * kstep;
;             const char* a3 = a2 + kstep; const char* b3 = b2 + kstep;
;             const unsigned xA0 = last ? nvA0 : vA0, xA1 = last ? nvA1 : vA1, xB0 = last ? nvB0 : vB0, xB1 = last ? nvB1 : vB1;
;     ...
;             PG8_BAR; PG8_WAIT_L(0); PG8_MMA(0, 1, At, B1); PG8_BAR;
;             PG8_LDA(At, 1, 1); PG8_STAGE(PG8_SA(1, 0), a3, xA0, xA1);
;             PG8_BAR; PG8_WAIT_L(0); PG8_MMA(1, 0, At, B0); PG8_BAR; PG8_SCHED;
;             PG8_STAGE(PG8_SB(1, 1), b3 + xhB, xB0, xB1);
;             PG8_WAIT_V(6); PG8_BAR; PG8_MMA(1, 1, At, B1); PG8_BAR;
	s_waitcnt lgkmcnt(0)
	v_mfma_f32_16x16x32_bf16 v[116:119], v[218:221], v[186:189], v[116:119]
	v_mfma_f32_16x16x32_bf16 v[112:115], v[226:229], v[186:189], v[112:115]
	v_mfma_f32_16x16x32_bf16 v[92:95], v[218:221], v[194:197], v[92:95]
	v_mfma_f32_16x16x32_bf16 v[88:91], v[226:229], v[194:197], v[88:91]
	v_mfma_f32_16x16x32_bf16 v[76:79], v[218:221], v[202:205], v[76:79]
	v_mfma_f32_16x16x32_bf16 v[72:75], v[226:229], v[202:205], v[72:75]
	v_mfma_f32_16x16x32_bf16 v[68:71], v[218:221], v[210:213], v[68:71]
	v_mfma_f32_16x16x32_bf16 v[64:67], v[226:229], v[210:213], v[64:67]
	v_mfma_f32_16x16x32_bf16 v[116:119], v[222:225], v[190:193], v[116:119]
	v_mfma_f32_16x16x32_bf16 v[112:115], v[230:233], v[190:193], v[112:115]
	v_mfma_f32_16x16x32_bf16 v[92:95], v[222:225], v[198:201], v[92:95]
	v_mfma_f32_16x16x32_bf16 v[88:91], v[230:233], v[198:201], v[88:91]
	v_mfma_f32_16x16x32_bf16 v[76:79], v[222:225], v[206:209], v[76:79]
	v_mfma_f32_16x16x32_bf16 v[72:75], v[230:233], v[206:209], v[72:75]
	v_mfma_f32_16x16x32_bf16 v[68:71], v[222:225], v[214:217], v[68:71]
	v_mfma_f32_16x16x32_bf16 v[64:67], v[230:233], v[214:217], v[64:67]
	s_barrier
	ds_read_b128 v[186:189], v148 offset:49152
	ds_read_b128 v[190:193], v148 offset:50176
	ds_read_b128 v[194:197], v148 offset:51200
	ds_read_b128 v[198:201], v148 offset:52224
	ds_read_b128 v[202:205], v148 offset:53248
	ds_read_b128 v[206:209], v148 offset:54272
	ds_read_b128 v[210:213], v148 offset:55296
	ds_read_b128 v[214:217], v148 offset:56320
	global_load_lds_dwordx4 v[138:139], off
	v_lshl_add_u64 v[138:139], v[236:237], 0, s[44:45]
	s_mov_b32 m0, s66
	s_nop 0
	global_load_lds_dwordx4 v[138:139], off
	s_barrier
	s_waitcnt lgkmcnt(0)
	v_mfma_f32_16x16x32_bf16 v[60:63], v[150:153], v[186:189], v[60:63]
	v_mfma_f32_16x16x32_bf16 v[56:59], v[158:161], v[186:189], v[56:59]
	v_mfma_f32_16x16x32_bf16 v[44:47], v[150:153], v[194:197], v[44:47]
	v_mfma_f32_16x16x32_bf16 v[40:43], v[158:161], v[194:197], v[40:43]
	v_mfma_f32_16x16x32_bf16 v[28:31], v[150:153], v[202:205], v[28:31]
	v_mfma_f32_16x16x32_bf16 v[24:27], v[158:161], v[202:205], v[24:27]
	v_mfma_f32_16x16x32_bf16 v[12:15], v[150:153], v[210:213], v[12:15]
	v_mfma_f32_16x16x32_bf16 v[8:11], v[158:161], v[210:213], v[8:11]
	v_mfma_f32_16x16x32_bf16 v[60:63], v[154:157], v[190:193], v[60:63]
	v_mfma_f32_16x16x32_bf16 v[56:59], v[182:185], v[190:193], v[56:59]
	v_mfma_f32_16x16x32_bf16 v[44:47], v[154:157], v[198:201], v[44:47]
	v_mfma_f32_16x16x32_bf16 v[40:43], v[182:185], v[198:201], v[40:43]
	v_mfma_f32_16x16x32_bf16 v[28:31], v[154:157], v[206:209], v[28:31]
	v_mfma_f32_16x16x32_bf16 v[24:27], v[182:185], v[206:209], v[24:27]
	v_mfma_f32_16x16x32_bf16 v[12:15], v[154:157], v[214:217], v[12:15]
	v_mfma_f32_16x16x32_bf16 v[8:11], v[182:185], v[214:217], v[8:11]
	s_barrier
	s_add_u32 s34, s34, 0x200080
	s_addc_u32 s35, s35, 0
	s_add_i32 s15, s38, s48
	v_lshl_add_u64 v[138:139], s[34:35], 0, v[142:143]
	s_mov_b32 m0, s15
	v_lshl_add_u64 v[134:135], s[34:35], 0, v[134:135]
	global_load_lds_dwordx4 v[138:139], off
	s_add_i32 m0, s15, 0x2000
	s_nop 0
	global_load_lds_dwordx4 v[134:135], off
	s_waitcnt vmcnt(6)
	s_barrier
	v_mfma_f32_16x16x32_bf16 v[52:55], v[218:221], v[186:189], v[52:55]
	v_mfma_f32_16x16x32_bf16 v[48:51], v[226:229], v[186:189], v[48:51]
	v_mfma_f32_16x16x32_bf16 v[36:39], v[218:221], v[194:197], v[36:39]
	v_mfma_f32_16x16x32_bf16 v[32:35], v[226:229], v[194:197], v[32:35]
	v_mfma_f32_16x16x32_bf16 v[20:23], v[218:221], v[202:205], v[20:23]
	v_mfma_f32_16x16x32_bf16 v[16:19], v[226:229], v[202:205], v[16:19]
	v_mfma_f32_16x16x32_bf16 v[4:7], v[218:221], v[210:213], v[4:7]
	v_mfma_f32_16x16x32_bf16 v[0:3], v[226:229], v[210:213], v[0:3]
	v_mfma_f32_16x16x32_bf16 v[52:55], v[222:225], v[190:193], v[52:55]
	v_mfma_f32_16x16x32_bf16 v[48:51], v[230:233], v[190:193], v[48:51]
	v_mfma_f32_16x16x32_bf16 v[36:39], v[222:225], v[198:201], v[36:39]
	v_mfma_f32_16x16x32_bf16 v[32:35], v[230:233], v[198:201], v[32:35]
	v_mfma_f32_16x16x32_bf16 v[20:23], v[222:225], v[206:209], v[20:23]
	v_mfma_f32_16x16x32_bf16 v[16:19], v[230:233], v[206:209], v[16:19]
	v_mfma_f32_16x16x32_bf16 v[4:7], v[222:225], v[214:217], v[4:7]
	v_mfma_f32_16x16x32_bf16 v[0:3], v[230:233], v[214:217], v[0:3]
	s_add_i32 s11, s11, 2
	s_add_u32 s24, s24, 0x100
	s_addc_u32 s25, s25, 0
	s_add_u32 s26, s26, 0x100
	s_addc_u32 s27, s27, 0
	s_cmpk_gt_u32 s11, 0x7d
	s_cbranch_scc1 .Lrot_exit_4
	s_cmpk_eq_i32 s11, 0x7c
	s_cselect_b64 s[38:39], -1, 0
	s_and_b64 vcc, exec, s[38:39]
	v_mov_b64_e32 v[134:135], v[130:131]
	v_mov_b64_e32 v[142:143], v[128:129]
	s_mov_b64 s[34:35], s[22:23]
	s_cbranch_vccnz .Lrot_join_4
	v_mov_b64_e32 v[134:135], v[132:133]
	v_mov_b64_e32 v[142:143], v[136:137]
	s_mov_b64 s[34:35], s[26:27]
